# scan A/C recurrences rewritten with scalar f32 FMAs (was packed ops with nop padding), MFMA nop pads trimmed to the required 8 states, merge phase 4 pieces in flight
# speedup vs baseline: 1.0152x; 1.0152x over previous
; template <class SEpi>
; __device__ __forceinline__ void sample_gemm(LAS unsigned char* lds, const bf16_t* A, const bf16_t* Bt, int K, const SEpi& E, int wave, int lane) {
;     ...
;         asm volatile("s_nop 15\n\ts_nop 15" : "+v"(acc[0]), "+v"(acc[1]), "+v"(acc[2]), "+v"(acc[3]));
; #pragma unroll
;         for (int c = 0; c < 4; ++c) red[(wave * 4 + c) * 64 + lane] = acc[c];
;         __syncthreads();
;         if (wave < 4) {
;             f32x4 t = red[wave * 64 + lane];
; #pragma unroll
;             for (int w = 1; w < 8; ++w) t += red[(w * 4 + wave) * 64 + lane];
;             float q = E.apply(t, row, 64 * cg + 16 * wave + 4 * fq, fq);
;             if (SEpi::HAS_SSQ) { q += __shfl_xor(q, 16); q += __shfl_xor(q, 32); if (fq == 0) P[wave * 16 + fr] = q; }
.LBB0_354:
	s_addk_i32 s31, 0x4000
	s_nop 7
	v_add_u32_e32 v16, s4, v30
	s_and_b64 vcc, exec, s[38:39]
	ds_write_b128 v16, v[0:3]
	ds_write_b128 v16, v[4:7] offset:1024
	ds_write_b128 v16, v[8:11] offset:2048
	ds_write_b128 v16, v[12:15] offset:3072
	s_waitcnt lgkmcnt(0)
	s_barrier
	s_cbranch_vccz .LBB0_358
	v_add_u32_e32 v10, s26, v30
	ds_read_b128 v[0:3], v10
	ds_read_b128 v[4:7], v10 offset:4096
	v_or_b32_e32 v8, s31, v161
	v_ashrrev_i32_e32 v9, 31, v8
	s_waitcnt lgkmcnt(0)
	v_pk_add_f32 v[6:7], v[2:3], v[6:7]
	v_pk_add_f32 v[4:5], v[0:1], v[4:5]
	ds_read_b128 v[0:3], v10 offset:8192
	s_waitcnt lgkmcnt(0)
	v_pk_add_f32 v[6:7], v[6:7], v[2:3]
	v_pk_add_f32 v[4:5], v[4:5], v[0:1]
	ds_read_b128 v[0:3], v10 offset:12288
	s_waitcnt lgkmcnt(0)
	v_pk_add_f32 v[6:7], v[6:7], v[2:3]
	v_pk_add_f32 v[4:5], v[4:5], v[0:1]
	ds_read_b128 v[0:3], v10 offset:16384
	s_waitcnt lgkmcnt(0)
	v_pk_add_f32 v[6:7], v[6:7], v[2:3]
	v_pk_add_f32 v[4:5], v[4:5], v[0:1]
	ds_read_b128 v[0:3], v10 offset:20480
	s_waitcnt lgkmcnt(0)
	v_pk_add_f32 v[6:7], v[6:7], v[2:3]
	v_pk_add_f32 v[4:5], v[4:5], v[0:1]
	ds_read_b128 v[0:3], v10 offset:24576
	s_waitcnt lgkmcnt(0)
	v_pk_add_f32 v[6:7], v[6:7], v[2:3]
	v_pk_add_f32 v[4:5], v[4:5], v[0:1]
	ds_read_b128 v[0:3], v10 offset:28672
	s_waitcnt lgkmcnt(0)
	v_pk_add_f32 v[2:3], v[6:7], v[2:3]
	v_pk_add_f32 v[0:1], v[4:5], v[0:1]
	v_or_b32_e32 v6, s30, v31
	v_lshlrev_b64 v[4:5], 11, v[8:9]
	v_lshl_add_u64 v[4:5], s[22:23], 0, v[4:5]
	v_lshlrev_b32_e32 v16, 1, v6
	v_lshl_add_u64 v[4:5], v[4:5], 0, v[16:17]
	global_load_dwordx2 v[6:7], v[4:5], off
	s_waitcnt vmcnt(0)
	v_lshlrev_b32_e32 v8, 16, v6
	v_and_b32_e32 v9, 0xffff0000, v6
	v_lshlrev_b32_e32 v6, 16, v7
	v_and_b32_e32 v7, 0xffff0000, v7
	v_pk_fma_f32 v[0:1], v[0:1], 0.5, v[8:9] op_sel_hi:[1,0,1]
	v_pk_fma_f32 v[2:3], v[2:3], 0.5, v[6:7] op_sel_hi:[1,0,1]
	v_cvt_pk_bf16_f32 v6, v0, v1
	v_mul_f32_e32 v1, v1, v1
	v_fmac_f32_e32 v1, v0, v0
	v_mul_f32_e32 v0, v3, v3
	v_cvt_pk_bf16_f32 v7, v2, v3
	v_fmac_f32_e32 v0, v2, v2
	v_and_b32_e32 v2, 64, v34
	v_add_f32_e32 v0, v1, v0
	v_xor_b32_e32 v1, 16, v34
	v_add_u32_e32 v2, 64, v2
	v_cmp_lt_i32_e32 vcc, v1, v2
	global_store_dwordx2 v[4:5], v[6:7], off
	s_nop 0
	v_cndmask_b32_e32 v1, v34, v1, vcc
	v_lshlrev_b32_e32 v1, 2, v1
	ds_bpermute_b32 v1, v1, v0
	s_waitcnt lgkmcnt(0)
	v_add_f32_e32 v0, v0, v1
	v_xor_b32_e32 v1, 32, v34
	v_cmp_lt_i32_e32 vcc, v1, v2
	s_nop 1
	v_cndmask_b32_e32 v1, v34, v1, vcc
	v_lshlrev_b32_e32 v1, 2, v1
	ds_bpermute_b32 v1, v1, v0
	s_and_saveexec_b64 s[50:51], s[72:73]
	s_cbranch_execz .LBB0_357
	s_waitcnt lgkmcnt(0)
	v_add_f32_e32 v0, v0, v1
	ds_write_b32 v32, v0 offset:32768

; __device__ __forceinline__ unsigned cvt_pk_bf16(float lo, float hi) { unsigned r; asm volatile("v_cvt_pk_bf16_f32 %0, %1, %2" : "=v"(r) : "v"(lo), "v"(hi)); return r; }
;     __device__ __forceinline__ float apply(const f32x4 acc, int row, int col, int fq) const {
;         bf16_t* bp = xb + (size_t)row * D + col; const u32x2 r = *(const u32x2*)bp; f32x4 o;
;         o[0] = __uint_as_float(r.x << 16); o[1] = __uint_as_float(r.x & 0xffff0000u); o[2] = __uint_as_float(r.y << 16); o[3] = __uint_as_float(r.y & 0xffff0000u);
;         o += acc * scale;
;         u32x2 w; w.x = cvt_pk_bf16(o[0], o[1]); w.y = cvt_pk_bf16(o[2], o[3]); *(u32x2*)bp = w;
;         return (o[0] * o[0] + o[1] * o[1]) + (o[2] * o[2] + o[3] * o[3]);
;     }
; template <class SEpi>
; __device__ __forceinline__ void sample_gemm(LAS unsigned char* lds, const bf16_t* A, const bf16_t* Bt, int K, const SEpi& E, int wave, int lane) {
;     ...
;         for (int k0 = 0; k0 < nks; k0 += 4) {
;             bf16x8 af[4], bf[4][4];
; #pragma unroll
;             for (int u = 0; u < 4; ++u) { const int ks = (k0 + u < nks) ? k0 + u : k0;
;                 af[u] = *(const bf16x8*)(ap + 32 * ks);
; #pragma unroll
;                 for (int c = 0; c < 4; ++c) bf[u][c] = *(const bf16x8*)(bp + (size_t)(16 * c) * K + 32 * ks); }
; #pragma unroll
;             for (int u = 0; u < 4; ++u) if (k0 + u < nks) {
; #pragma unroll
;                 for (int c = 0; c < 4; ++c) acc[c] = __builtin_amdgcn_mfma_f32_16x16x32_bf16(bf[u][c], af[u], acc[c], 0, 0, 0); }
;         }
;         asm volatile("s_nop 15\n\ts_nop 15" : "+v"(acc[0]), "+v"(acc[1]), "+v"(acc[2]), "+v"(acc[3]));
; #pragma unroll
;         for (int c = 0; c < 4; ++c) red[(wave * 4 + c) * 64 + lane] = acc[c];
;         __syncthreads();
;         if (wave < 4) {
;             f32x4 t = red[wave * 64 + lane];
; #pragma unroll
;             for (int w = 1; w < 8; ++w) t += red[(w * 4 + wave) * 64 + lane];
;             float q = E.apply(t, row, 64 * cg + 16 * wave + 4 * fq, fq);
;             if (SEpi::HAS_SSQ) { q += __shfl_xor(q, 16); q += __shfl_xor(q, 32); if (fq == 0) P[wave * 16 + fr] = q; }
;         }
;         __syncthreads();
;         if (SEpi::HAS_SSQ && wave == 0 && lane < 16) E.ssq_out[(size_t)(MP + 16 * rt + lane) * 16 + cg] = (P[lane] + P[16 + lane]) + (P[32 + lane] + P[48 + lane]);
.LBB0_801:
	s_and_b32 s26, s4, 15
	s_lshl_b32 s28, s26, 6
	v_or_b32_e32 v0, s28, v161
	v_mul_u32_u24_e32 v0, 0x300, v0
	v_lshlrev_b32_e32 v0, 1, v0
	v_lshl_add_u64 v[42:43], v[4:5], 0, v[0:1]
	v_add_co_u32_e32 v44, vcc, 0x6000, v42
	s_and_b32 s27, s4, -16
	s_nop 0
	v_addc_co_u32_e32 v45, vcc, 0, v43, vcc
	v_add_co_u32_e32 v46, vcc, 0xc000, v42
	s_addk_i32 s27, 0x4000
	s_nop 0
	v_addc_co_u32_e32 v47, vcc, 0, v43, vcc
	v_add_co_u32_e32 v48, vcc, 0x12000, v42
	v_or_b32_e32 v6, s27, v161
	s_movk_i32 s6, 0x600
	v_addc_co_u32_e32 v49, vcc, 0, v43, vcc
	v_mad_i64_i32 v[40:41], s[6:7], v6, s6, v[2:3]
	global_load_dwordx4 v[12:15], v[42:43], off
	global_load_dwordx4 v[16:19], v[44:45], off
	global_load_dwordx4 v[20:23], v[40:41], off
	global_load_dwordx4 v[24:27], v[46:47], off
	global_load_dwordx4 v[28:31], v[40:41], off offset:64
	global_load_dwordx4 v[36:39], v[48:49], off
	global_load_dwordx4 v[32:35], v[42:43], off offset:64
	s_and_b64 vcc, exec, s[44:45]
	s_waitcnt vmcnt(4)
	v_mfma_f32_16x16x32_bf16 v[16:19], v[16:19], v[20:23], 0
	v_mfma_f32_16x16x32_bf16 v[12:15], v[12:15], v[20:23], 0
	s_waitcnt vmcnt(3)
	v_mfma_f32_16x16x32_bf16 v[24:27], v[24:27], v[20:23], 0
	s_waitcnt vmcnt(1)
	v_mfma_f32_16x16x32_bf16 v[20:23], v[36:39], v[20:23], 0
	global_load_dwordx4 v[36:39], v[46:47], off offset:64
	s_waitcnt vmcnt(0)
	v_mfma_f32_16x16x32_bf16 v[24:27], v[36:39], v[28:31], v[24:27]
	global_load_dwordx4 v[36:39], v[40:41], off offset:128
	v_mfma_f32_16x16x32_bf16 v[12:15], v[32:35], v[28:31], v[12:15]
	global_load_dwordx4 v[32:35], v[44:45], off offset:64
	s_waitcnt vmcnt(0)
	v_mfma_f32_16x16x32_bf16 v[16:19], v[32:35], v[28:31], v[16:19]
	global_load_dwordx4 v[32:35], v[42:43], off offset:128
	s_waitcnt vmcnt(0)
	v_mfma_f32_16x16x32_bf16 v[12:15], v[32:35], v[36:39], v[12:15]
	global_load_dwordx4 v[32:35], v[48:49], off offset:64
	s_waitcnt vmcnt(0)
	v_mfma_f32_16x16x32_bf16 v[20:23], v[32:35], v[28:31], v[20:23]
	global_load_dwordx4 v[28:31], v[44:45], off offset:128
	s_waitcnt vmcnt(0)
	v_mfma_f32_16x16x32_bf16 v[16:19], v[28:31], v[36:39], v[16:19]
	global_load_dwordx4 v[28:31], v[46:47], off offset:128
	s_waitcnt vmcnt(0)
	v_mfma_f32_16x16x32_bf16 v[24:27], v[28:31], v[36:39], v[24:27]
	global_load_dwordx4 v[28:31], v[48:49], off offset:128
	s_waitcnt vmcnt(0)
	v_mfma_f32_16x16x32_bf16 v[20:23], v[28:31], v[36:39], v[20:23]
	s_nop 7
	ds_write_b128 v10, v[12:15]
	s_nop 0
	ds_write_b128 v10, v[16:19] offset:1024
	s_nop 1
	ds_write_b128 v10, v[24:27] offset:2048
	s_nop 1
	ds_write_b128 v10, v[20:23] offset:3072
	s_waitcnt lgkmcnt(0)
	s_barrier
	s_cbranch_vccnz .LBB0_805
	ds_read_b128 v[12:15], v11
	ds_read_b128 v[16:19], v11 offset:4096
	v_ashrrev_i32_e32 v7, 31, v6
	v_or_b32_e32 v0, s28, v8
	v_lshlrev_b64 v[6:7], 11, v[6:7]
	v_lshl_add_u64 v[6:7], s[22:23], 0, v[6:7]
	s_waitcnt lgkmcnt(0)
	v_pk_add_f32 v[18:19], v[14:15], v[18:19]
	v_pk_add_f32 v[16:17], v[12:13], v[16:17]
	ds_read_b128 v[12:15], v11 offset:8192
	v_lshlrev_b32_e32 v0, 1, v0
	v_lshl_add_u64 v[6:7], v[6:7], 0, v[0:1]
	s_waitcnt lgkmcnt(0)
	v_pk_add_f32 v[18:19], v[18:19], v[14:15]
	v_pk_add_f32 v[16:17], v[16:17], v[12:13]
	ds_read_b128 v[12:15], v11 offset:12288
	s_waitcnt lgkmcnt(0)
	v_pk_add_f32 v[18:19], v[18:19], v[14:15]
	v_pk_add_f32 v[16:17], v[16:17], v[12:13]
	ds_read_b128 v[12:15], v11 offset:16384
	s_waitcnt lgkmcnt(0)
	v_pk_add_f32 v[18:19], v[18:19], v[14:15]
	v_pk_add_f32 v[16:17], v[16:17], v[12:13]
	ds_read_b128 v[12:15], v11 offset:20480
	s_waitcnt lgkmcnt(0)
	v_pk_add_f32 v[18:19], v[18:19], v[14:15]
	v_pk_add_f32 v[16:17], v[16:17], v[12:13]
	ds_read_b128 v[12:15], v11 offset:24576
	s_waitcnt lgkmcnt(0)
	v_pk_add_f32 v[18:19], v[18:19], v[14:15]
	v_pk_add_f32 v[16:17], v[16:17], v[12:13]
	ds_read_b128 v[12:15], v11 offset:28672
	s_waitcnt lgkmcnt(0)
	v_pk_add_f32 v[12:13], v[16:17], v[12:13]
	global_load_dwordx2 v[16:17], v[6:7], off
	v_pk_add_f32 v[14:15], v[18:19], v[14:15]
	s_waitcnt vmcnt(0)
	v_lshlrev_b32_e32 v18, 16, v16
	v_and_b32_e32 v19, 0xffff0000, v16
	v_lshlrev_b32_e32 v16, 16, v17
	v_and_b32_e32 v17, 0xffff0000, v17
	v_pk_add_f32 v[14:15], v[14:15], v[16:17]
	v_pk_add_f32 v[12:13], v[12:13], v[18:19]
	s_nop 0
	v_cvt_pk_bf16_f32 v16, v12, v13
	v_cvt_pk_bf16_f32 v17, v14, v15
	global_store_dwordx2 v[6:7], v[16:17], off
	v_mul_f32_e32 v0, v13, v13
	v_mul_f32_e32 v6, v15, v15
	v_fmac_f32_e32 v0, v12, v12
	v_fmac_f32_e32 v6, v14, v14
	v_add_f32_e32 v0, v0, v6
	ds_bpermute_b32 v6, v112, v0
	s_waitcnt lgkmcnt(0)
	v_add_f32_e32 v0, v0, v6
	ds_bpermute_b32 v6, v113, v0
	s_and_saveexec_b64 s[46:47], s[30:31]
	s_cbranch_execz .LBB0_804
	s_waitcnt lgkmcnt(0)
	v_add_f32_e32 v0, v0, v6
	ds_write_b32 v9, v0 offset:32768

; __device__ __forceinline__ unsigned cvt_pk_bf16(float lo, float hi) { unsigned r; asm volatile("v_cvt_pk_bf16_f32 %0, %1, %2" : "=v"(r) : "v"(lo), "v"(hi)); return r; }
;     __device__ __forceinline__ float apply(const f32x4 acc, int row, int col, int fq) const {
;         bf16_t* bp = xb + (size_t)row * D + col; const u32x2 r = *(const u32x2*)bp; f32x4 o;
;         o[0] = __uint_as_float(r.x << 16); o[1] = __uint_as_float(r.x & 0xffff0000u); o[2] = __uint_as_float(r.y << 16); o[3] = __uint_as_float(r.y & 0xffff0000u);
;         o += acc * scale;
;         u32x2 w; w.x = cvt_pk_bf16(o[0], o[1]); w.y = cvt_pk_bf16(o[2], o[3]); *(u32x2*)bp = w;
;         return (o[0] * o[0] + o[1] * o[1]) + (o[2] * o[2] + o[3] * o[3]);
;     }
; template <class SEpi>
; __device__ __forceinline__ void sample_gemm(LAS unsigned char* lds, const bf16_t* A, const bf16_t* Bt, int K, const SEpi& E, int wave, int lane) {
;     ...
;         for (int c = 0; c < 4; ++c) red[(wave * 4 + c) * 64 + lane] = acc[c];
;         __syncthreads();
;         if (wave < 4) {
;             f32x4 t = red[wave * 64 + lane];
; #pragma unroll
;             for (int w = 1; w < 8; ++w) t += red[(w * 4 + wave) * 64 + lane];
;             float q = E.apply(t, row, 64 * cg + 16 * wave + 4 * fq, fq);
;             if (SEpi::HAS_SSQ) { q += __shfl_xor(q, 16); q += __shfl_xor(q, 32); if (fq == 0) P[wave * 16 + fr] = q; }
;         }
;         __syncthreads();
;         if (SEpi::HAS_SSQ && wave == 0 && lane < 16) E.ssq_out[(size_t)(MP + 16 * rt + lane) * 16 + cg] = (P[lane] + P[16 + lane]) + (P[32 + lane] + P[48 + lane]);
.LBB0_1043:
	s_addk_i32 s31, 0x4000
	s_nop 7
	v_add_u32_e32 v16, s4, v30
	s_and_b64 vcc, exec, s[38:39]
	ds_write_b128 v16, v[0:3]
	ds_write_b128 v16, v[4:7] offset:1024
	ds_write_b128 v16, v[8:11] offset:2048
	ds_write_b128 v16, v[12:15] offset:3072
	s_waitcnt lgkmcnt(0)
	s_barrier
	s_cbranch_vccz .LBB0_1047
	v_add_u32_e32 v10, s26, v30
	ds_read_b128 v[0:3], v10
	ds_read_b128 v[4:7], v10 offset:4096
	v_or_b32_e32 v8, s31, v161
	v_ashrrev_i32_e32 v9, 31, v8
	s_waitcnt lgkmcnt(0)
	v_pk_add_f32 v[6:7], v[2:3], v[6:7]
	v_pk_add_f32 v[4:5], v[0:1], v[4:5]
	ds_read_b128 v[0:3], v10 offset:8192
	s_waitcnt lgkmcnt(0)
	v_pk_add_f32 v[6:7], v[6:7], v[2:3]
	v_pk_add_f32 v[4:5], v[4:5], v[0:1]
	ds_read_b128 v[0:3], v10 offset:12288
	s_waitcnt lgkmcnt(0)
	v_pk_add_f32 v[6:7], v[6:7], v[2:3]
	v_pk_add_f32 v[4:5], v[4:5], v[0:1]
	ds_read_b128 v[0:3], v10 offset:16384
	s_waitcnt lgkmcnt(0)
	v_pk_add_f32 v[6:7], v[6:7], v[2:3]
	v_pk_add_f32 v[4:5], v[4:5], v[0:1]
	ds_read_b128 v[0:3], v10 offset:20480
	s_waitcnt lgkmcnt(0)
	v_pk_add_f32 v[6:7], v[6:7], v[2:3]
	v_pk_add_f32 v[4:5], v[4:5], v[0:1]
	ds_read_b128 v[0:3], v10 offset:24576
	s_waitcnt lgkmcnt(0)
	v_pk_add_f32 v[6:7], v[6:7], v[2:3]
	v_pk_add_f32 v[4:5], v[4:5], v[0:1]
	ds_read_b128 v[0:3], v10 offset:28672
	s_waitcnt lgkmcnt(0)
	v_pk_add_f32 v[2:3], v[6:7], v[2:3]
	v_pk_add_f32 v[0:1], v[4:5], v[0:1]
	v_or_b32_e32 v6, s30, v31
	v_lshlrev_b64 v[4:5], 11, v[8:9]
	v_lshl_add_u64 v[4:5], s[22:23], 0, v[4:5]
	v_lshlrev_b32_e32 v16, 1, v6
	v_lshl_add_u64 v[4:5], v[4:5], 0, v[16:17]
	global_load_dwordx2 v[6:7], v[4:5], off
	s_waitcnt vmcnt(0)
	v_lshlrev_b32_e32 v8, 16, v6
	v_and_b32_e32 v9, 0xffff0000, v6
	v_lshlrev_b32_e32 v6, 16, v7
	v_and_b32_e32 v7, 0xffff0000, v7
	v_pk_fma_f32 v[0:1], v[0:1], 0.5, v[8:9] op_sel_hi:[1,0,1]
	v_pk_fma_f32 v[2:3], v[2:3], 0.5, v[6:7] op_sel_hi:[1,0,1]
	v_cvt_pk_bf16_f32 v6, v0, v1
	v_mul_f32_e32 v1, v1, v1
	v_fmac_f32_e32 v1, v0, v0
	v_mul_f32_e32 v0, v3, v3
	v_fmac_f32_e32 v0, v2, v2
	v_add_f32_e32 v0, v1, v0
	ds_bpermute_b32 v1, v112, v0
	v_cvt_pk_bf16_f32 v7, v2, v3
	global_store_dwordx2 v[4:5], v[6:7], off
	s_waitcnt lgkmcnt(0)
	v_add_f32_e32 v0, v0, v1
	ds_bpermute_b32 v1, v113, v0
	s_and_saveexec_b64 s[46:47], s[44:45]
	s_cbranch_execz .LBB0_1046
	s_waitcnt lgkmcnt(0)
	v_add_f32_e32 v0, v0, v1
	ds_write_b32 v32, v0 offset:32768

;     __device__ __forceinline__ float apply(const f32x4 acc, int row, int col, int fq) const {
;         const f32x4 p = *(const f32x4*)(ssq + (size_t)row * 16 + 4 * fq); float t = (p[0] + p[1]) + (p[2] + p[3]); t += __shfl_xor(t, 16); t += __shfl_xor(t, 32);
;         const float sc = rsqrtf(t * (1.0f / D) + NORM_EPS);
;         *(f32x4*)(ubuf + (size_t)row * D + col) = acc * sc; return 0.f;
;     }
; template <class SEpi>
; __device__ __forceinline__ void sample_gemm(LAS unsigned char* lds, const bf16_t* A, const bf16_t* Bt, int K, const SEpi& E, int wave, int lane) {
;     ...
;         for (int k0 = 0; k0 < nks; k0 += 4) {
;             bf16x8 af[4], bf[4][4];
; #pragma unroll
;             for (int u = 0; u < 4; ++u) { const int ks = (k0 + u < nks) ? k0 + u : k0;
;                 af[u] = *(const bf16x8*)(ap + 32 * ks);
; #pragma unroll
;                 for (int c = 0; c < 4; ++c) bf[u][c] = *(const bf16x8*)(bp + (size_t)(16 * c) * K + 32 * ks); }
; #pragma unroll
;             for (int u = 0; u < 4; ++u) if (k0 + u < nks) {
; #pragma unroll
;                 for (int c = 0; c < 4; ++c) acc[c] = __builtin_amdgcn_mfma_f32_16x16x32_bf16(bf[u][c], af[u], acc[c], 0, 0, 0); }
;         }
;         asm volatile("s_nop 15\n\ts_nop 15" : "+v"(acc[0]), "+v"(acc[1]), "+v"(acc[2]), "+v"(acc[3]));
; #pragma unroll
;         for (int c = 0; c < 4; ++c) red[(wave * 4 + c) * 64 + lane] = acc[c];
;         __syncthreads();
;         if (wave < 4) {
;             f32x4 t = red[wave * 64 + lane];
; #pragma unroll
;             for (int w = 1; w < 8; ++w) t += red[(w * 4 + wave) * 64 + lane];
;             float q = E.apply(t, row, 64 * cg + 16 * wave + 4 * fq, fq);
;             if (SEpi::HAS_SSQ) { q += __shfl_xor(q, 16); q += __shfl_xor(q, 32); if (fq == 0) P[wave * 16 + fr] = q; }
;         }
;         __syncthreads();
;         if (SEpi::HAS_SSQ && wave == 0 && lane < 16) E.ssq_out[(size_t)(MP + 16 * rt + lane) * 16 + cg] = (P[lane] + P[16 + lane]) + (P[32 + lane] + P[48 + lane]);
.LBB0_1402:
	s_and_b32 s29, s26, 0x3c0
	v_or_b32_e32 v0, s29, v161
	v_lshlrev_b32_e32 v0, 11, v0
	v_lshl_add_u64 v[46:47], v[4:5], 0, v[0:1]
	v_add_co_u32_e32 v50, vcc, 0x8000, v46
	s_and_b32 s6, s28, -16
	s_nop 0
	v_addc_co_u32_e32 v51, vcc, 0, v47, vcc
	v_add_u32_e32 v8, s6, v163
	global_load_dwordx4 v[14:17], v[46:47], off
	v_add_co_u32_e32 v52, vcc, 0x10000, v46
	v_ashrrev_i32_e32 v9, 31, v8
	s_nop 0
	v_addc_co_u32_e32 v53, vcc, 0, v47, vcc
	v_lshlrev_b64 v[18:19], 11, v[8:9]
	v_add_co_u32_e32 v54, vcc, 0x18000, v46
	v_lshl_add_u64 v[48:49], v[2:3], 0, v[18:19]
	s_nop 0
	v_addc_co_u32_e32 v55, vcc, 0, v47, vcc
	global_load_dwordx4 v[18:21], v[48:49], off
	global_load_dwordx4 v[22:25], v[50:51], off
	global_load_dwordx4 v[26:29], v[52:53], off
	global_load_dwordx4 v[30:33], v[46:47], off offset:64
	global_load_dwordx4 v[38:41], v[54:55], off
	global_load_dwordx4 v[34:37], v[48:49], off offset:64
	s_and_b64 vcc, exec, s[46:47]
	s_waitcnt vmcnt(0)
	v_mfma_f32_16x16x32_bf16 v[26:29], v[26:29], v[18:21], 0
	v_mfma_f32_16x16x32_bf16 v[14:17], v[14:17], v[18:21], 0
	v_mfma_f32_16x16x32_bf16 v[22:25], v[22:25], v[18:21], 0
	v_mfma_f32_16x16x32_bf16 v[18:21], v[38:41], v[18:21], 0
	global_load_dwordx4 v[38:41], v[52:53], off offset:64
	v_mfma_f32_16x16x32_bf16 v[14:17], v[30:33], v[34:37], v[14:17]
	global_load_dwordx4 v[30:33], v[50:51], off offset:64
	s_waitcnt vmcnt(0)
	v_mfma_f32_16x16x32_bf16 v[22:25], v[30:33], v[34:37], v[22:25]
	global_load_dwordx4 v[30:33], v[46:47], off offset:128
	global_load_dwordx4 v[42:45], v[48:49], off offset:128
	v_mfma_f32_16x16x32_bf16 v[26:29], v[38:41], v[34:37], v[26:29]
	global_load_dwordx4 v[38:41], v[54:55], off offset:64
	s_waitcnt vmcnt(1)
	v_mfma_f32_16x16x32_bf16 v[14:17], v[30:33], v[42:45], v[14:17]
	global_load_dwordx4 v[30:33], v[50:51], off offset:128
	s_waitcnt vmcnt(1)
	v_mfma_f32_16x16x32_bf16 v[18:21], v[38:41], v[34:37], v[18:21]
	global_load_dwordx4 v[34:37], v[52:53], off offset:128
	s_waitcnt vmcnt(1)
	v_mfma_f32_16x16x32_bf16 v[22:25], v[30:33], v[42:45], v[22:25]
	global_load_dwordx4 v[30:33], v[46:47], off offset:192
	s_waitcnt vmcnt(1)
	v_mfma_f32_16x16x32_bf16 v[26:29], v[34:37], v[42:45], v[26:29]
	global_load_dwordx4 v[34:37], v[48:49], off offset:192
	s_waitcnt vmcnt(0)
	v_mfma_f32_16x16x32_bf16 v[14:17], v[30:33], v[34:37], v[14:17]
	global_load_dwordx4 v[30:33], v[54:55], off offset:128
	s_waitcnt vmcnt(0)
	v_mfma_f32_16x16x32_bf16 v[18:21], v[30:33], v[42:45], v[18:21]
	global_load_dwordx4 v[30:33], v[50:51], off offset:192
	s_waitcnt vmcnt(0)
	v_mfma_f32_16x16x32_bf16 v[22:25], v[30:33], v[34:37], v[22:25]
	global_load_dwordx4 v[30:33], v[52:53], off offset:192
	s_waitcnt vmcnt(0)
	v_mfma_f32_16x16x32_bf16 v[26:29], v[30:33], v[34:37], v[26:29]
	global_load_dwordx4 v[30:33], v[54:55], off offset:192
	s_waitcnt vmcnt(0)
	v_mfma_f32_16x16x32_bf16 v[18:21], v[30:33], v[34:37], v[18:21]
	s_nop 7
	ds_write_b128 v10, v[14:17]
	s_nop 0
	ds_write_b128 v10, v[22:25] offset:1024
	s_nop 1
	ds_write_b128 v10, v[26:29] offset:2048
	s_nop 1
	ds_write_b128 v10, v[18:21] offset:3072
	s_waitcnt lgkmcnt(0)
	s_barrier
	s_cbranch_vccnz .LBB0_1401
	v_add_u32_e32 v0, s4, v197
	ds_read_b128 v[14:17], v0
	ds_read_b128 v[18:21], v0 offset:4096
	s_mov_b32 s6, 0x800000
	v_or_b32_e32 v13, s29, v196
	s_waitcnt lgkmcnt(0)
	v_pk_add_f32 v[20:21], v[16:17], v[20:21]
	v_pk_add_f32 v[18:19], v[14:15], v[18:19]
	ds_read_b128 v[14:17], v0 offset:8192
	s_waitcnt lgkmcnt(0)
	v_pk_add_f32 v[20:21], v[20:21], v[16:17]
	v_pk_add_f32 v[18:19], v[18:19], v[14:15]
	ds_read_b128 v[14:17], v0 offset:12288
	s_waitcnt lgkmcnt(0)
	v_pk_add_f32 v[20:21], v[20:21], v[16:17]
	v_pk_add_f32 v[18:19], v[18:19], v[14:15]
	ds_read_b128 v[14:17], v0 offset:16384
	s_waitcnt lgkmcnt(0)
	v_pk_add_f32 v[20:21], v[20:21], v[16:17]
	v_pk_add_f32 v[18:19], v[18:19], v[14:15]
	ds_read_b128 v[14:17], v0 offset:20480
	s_waitcnt lgkmcnt(0)
	v_pk_add_f32 v[20:21], v[20:21], v[16:17]
	v_pk_add_f32 v[18:19], v[18:19], v[14:15]
	ds_read_b128 v[14:17], v0 offset:24576
	s_waitcnt lgkmcnt(0)
	v_pk_add_f32 v[20:21], v[20:21], v[16:17]
	v_pk_add_f32 v[18:19], v[18:19], v[14:15]
	ds_read_b128 v[14:17], v0 offset:28672
	s_waitcnt lgkmcnt(0)
	v_pk_add_f32 v[18:19], v[18:19], v[14:15]
	v_lshlrev_b64 v[14:15], 6, v[8:9]
	v_lshl_add_u64 v[14:15], v[6:7], 0, v[14:15]
	v_pk_add_f32 v[20:21], v[20:21], v[16:17]
	global_load_dwordx4 v[14:17], v[14:15], off
	v_lshlrev_b64 v[8:9], 12, v[8:9]
	v_lshl_add_u64 v[8:9], s[24:25], 0, v[8:9]
	s_waitcnt vmcnt(0)
	v_mov_b32_e32 v22, v15
	v_mov_b32_e32 v23, v16
	v_mov_b32_e32 v15, v17
	v_pk_add_f32 v[14:15], v[22:23], v[14:15]
	s_nop 0
	v_add_f32_e32 v0, v14, v15
	v_and_b32_e32 v15, 64, v12
	v_xor_b32_e32 v14, 16, v12
	v_add_u32_e32 v15, 64, v15
	v_cmp_lt_i32_e32 vcc, v14, v15
	s_nop 1
	v_cndmask_b32_e32 v14, v12, v14, vcc
	v_lshlrev_b32_e32 v14, 2, v14
	ds_bpermute_b32 v14, v14, v0
	s_waitcnt lgkmcnt(0)
	v_add_f32_e32 v0, v0, v14
	v_xor_b32_e32 v14, 32, v12
	v_cmp_lt_i32_e32 vcc, v14, v15
	s_nop 1
	v_cndmask_b32_e32 v14, v12, v14, vcc
	v_lshlrev_b32_e32 v14, 2, v14
	ds_bpermute_b32 v14, v14, v0
	s_waitcnt lgkmcnt(0)
	v_add_f32_e32 v0, v0, v14
	v_fmamk_f32 v0, v0, 0x3a800000, v11
	v_cmp_gt_f32_e32 vcc, s6, v0
	v_mul_f32_e32 v14, 0x4b800000, v0
	s_nop 0
	v_cndmask_b32_e32 v0, v0, v14, vcc
	v_rsq_f32_e32 v0, v0
	s_nop 0
	v_mul_f32_e32 v14, 0x45800000, v0
	v_cndmask_b32_e32 v0, v0, v14, vcc
	v_pk_mul_f32 v[16:17], v[20:21], v[0:1] op_sel_hi:[1,0]
	v_pk_mul_f32 v[14:15], v[18:19], v[0:1] op_sel_hi:[1,0]
	v_lshlrev_b32_e32 v0, 2, v13
	v_lshl_add_u64 v[8:9], v[8:9], 0, v[0:1]
	global_store_dwordx4 v[8:9], v[14:17], off
	s_branch .LBB0_1401

; #define LAS __attribute__((address_space(3)))
; template <bool PROJECT> ...
;     ...
;             const f32x4 a0 = *(const LAS f32x4*)(Ul + c * 16 + c0), a1 = *(const LAS f32x4*)(Ul + c * 16 + c0 + 4);
;             u32x4 wh; wh.x = cvt_pk_bf16(a0[0], a0[1]); wh.y = cvt_pk_bf16(a0[2], a0[3]); wh.z = cvt_pk_bf16(a1[0], a1[1]); wh.w = cvt_pk_bf16(a1[2], a1[3]);
;             u32x4 wl;
;             wl.x = cvt_pk_bf16(a0[0] - __uint_as_float(wh.x << 16), a0[1] - __uint_as_float(wh.x & 0xffff0000u)); wl.y = cvt_pk_bf16(a0[2] - __uint_as_float(wh.y << 16), a0[3] - __uint_as_float(wh.y & 0xffff0000u));
;             wl.z = cvt_pk_bf16(a1[0] - __uint_as_float(wh.z << 16), a1[1] - __uint_as_float(wh.z & 0xffff0000u)); wl.w = cvt_pk_bf16(a1[2] - __uint_as_float(wh.w << 16), a1[3] - __uint_as_float(wh.w & 0xffff0000u));
;             u32x4 wsel; wsel.x = part ? wl.x : wh.x; wsel.y = part ? wl.y : wh.y; wsel.z = part ? wl.z : wh.z; wsel.w = part ? wl.w : wh.w;
;             const bf16x8 aop = __builtin_bit_cast(bf16x8, wsel);
;             f32x4 br[4], bi[4];
; #pragma unroll
;             for (int i = 0; i < 4; ++i) {
;                 f32x4 zr = (f32x4){0.f, 0.f, 0.f, 0.f}, zi = zr;
;                 br[i] = __builtin_amdgcn_mfma_f32_16x16x32_bf16(aop, bop[0][i], zr, 0, 0, 0); bi[i] = __builtin_amdgcn_mfma_f32_16x16x32_bf16(aop, bop[1][i], zi, 0, 0, 0);
;             }
;             asm volatile("s_nop 15\n\ts_nop 15\n\ts_nop 15\n\ts_nop 15" : "+v"(br[0]), "+v"(br[1]), "+v"(br[2]), "+v"(br[3]), "+v"(bi[0]), "+v"(bi[1]), "+v"(bi[2]), "+v"(bi[3]), "+v"(wsel));
; #pragma unroll
;             for (int i = 0; i < 4; ++i)
; #pragma unroll
;                 for (int j = 0; j < 4; ++j) *(LAS f32x2v*)(BUl + (4 * tq + j) * BU_PITCH + 2 * (16 * i + c)) = (f32x2v){br[i][j], bi[i][j]};
;             asm volatile("s_waitcnt lgkmcnt(0)" ::: "memory"); __builtin_amdgcn_wave_barrier();
;         }
;         {
;             float bur[16], bui[16];
; #pragma unroll
;             for (int t = 0; t < 16; ++t) { const f32x2v bu = *(const LAS f32x2v*)(BUl + t * BU_PITCH + 2 * lane); bur[t] = bu.x; bui[t] = bu.y; }
; #pragma unroll
;             for (int t = 0; t < 16; ++t) {
;                 const float nre = lre * hre - lim * him + bur[t], nim = lre * him + lim * hre + bui[t];
;                 if (t < nsub) { hre = nre; him = nim; }
.LBB0_1464:
	v_add_u32_e32 v49, s28, v74
	ds_read_b128 v[76:79], v49
	ds_read_b128 v[80:83], v49 offset:16
	s_addk_i32 s28, 0x400
	s_cmpk_eq_i32 s28, 0x1000
	s_waitcnt lgkmcnt(0)
	v_cvt_pk_bf16_f32 v49, v76, v77
	s_nop 0
	v_lshlrev_b32_e32 v86, 16, v49
	v_sub_f32_e32 v76, v76, v86
	v_and_b32_e32 v86, 0xffff0000, v49
	v_sub_f32_e32 v77, v77, v86
	v_cvt_pk_bf16_f32 v75, v78, v79
	v_cvt_pk_bf16_f32 v84, v80, v81
	v_cvt_pk_bf16_f32 v85, v82, v83
	v_cvt_pk_bf16_f32 v76, v76, v77
	s_nop 0
	v_lshlrev_b32_e32 v77, 16, v75
	v_sub_f32_e32 v77, v78, v77
	v_and_b32_e32 v78, 0xffff0000, v75
	v_sub_f32_e32 v78, v79, v78
	v_cvt_pk_bf16_f32 v77, v77, v78
	v_lshlrev_b32_e32 v78, 16, v84
	v_and_b32_e32 v79, 0xffff0000, v84
	v_sub_f32_e32 v78, v80, v78
	v_sub_f32_e32 v79, v81, v79
	v_cvt_pk_bf16_f32 v78, v78, v79
	v_lshlrev_b32_e32 v79, 16, v85
	v_sub_f32_e32 v79, v82, v79
	v_and_b32_e32 v80, 0xffff0000, v85
	v_sub_f32_e32 v80, v83, v80
	v_cvt_pk_bf16_f32 v79, v79, v80
	v_cndmask_b32_e64 v76, v76, v49, s[46:47]
	v_cndmask_b32_e64 v77, v77, v75, s[46:47]
	v_cndmask_b32_e64 v78, v78, v84, s[46:47]
	v_cndmask_b32_e64 v79, v79, v85, s[46:47]
	v_add_u32_e32 v49, v169, v171
	v_add_u32_e32 v75, 0x2000, v49
	v_mfma_f32_16x16x32_bf16 v[80:83], v[76:79], v[0:3], 0
	v_add_u32_e32 v49, 0x2800, v49
	v_mfma_f32_16x16x32_bf16 v[84:87], v[76:79], v[4:7], 0
	v_mfma_f32_16x16x32_bf16 v[88:91], v[76:79], v[8:11], 0
	v_mfma_f32_16x16x32_bf16 v[92:95], v[76:79], v[12:15], 0
	v_mfma_f32_16x16x32_bf16 v[96:99], v[76:79], v[16:19], 0
	v_mfma_f32_16x16x32_bf16 v[100:103], v[76:79], v[20:23], 0
	v_mfma_f32_16x16x32_bf16 v[104:107], v[76:79], v[24:27], 0
	v_mfma_f32_16x16x32_bf16 v[108:111], v[76:79], v[28:31], 0
	s_nop 7
	s_nop 0
	v_mov_b32_e32 v76, v80
	v_mov_b32_e32 v77, v84
	v_mov_b32_e32 v84, v81
	v_mov_b32_e32 v80, v88
	v_mov_b32_e32 v81, v92
	v_mov_b32_e32 v78, v82
	v_mov_b32_e32 v79, v86
	ds_write2_b64 v75, v[76:77], v[80:81] offset0:32 offset1:48
	v_mov_b32_e32 v76, v90
	v_mov_b32_e32 v77, v94
	ds_write2_b64 v75, v[78:79], v[76:77] offset0:162 offset1:178
	v_mov_b32_e32 v76, v96
	v_mov_b32_e32 v77, v100
	v_mov_b32_e32 v80, v104
	v_mov_b32_e32 v81, v108
	v_mov_b32_e32 v79, v102
	v_mov_b32_e32 v102, v99
	ds_write2_b64 v75, v[76:77], v[80:81] offset0:64 offset1:80
	v_mov_b32_e32 v77, v110
	v_mov_b32_e32 v110, v107
	v_mov_b32_e32 v86, v83
	v_mov_b32_e32 v92, v89
	v_mov_b32_e32 v94, v91
	v_mov_b32_e32 v100, v97
	v_mov_b32_e32 v78, v98
	v_mov_b32_e32 v108, v105
	v_mov_b32_e32 v76, v106
	ds_write2_b64 v49, v[102:103], v[110:111] offset0:3 offset1:19
	v_add_u32_e32 v49, s27, v166
	ds_write2_b64 v75, v[84:85], v[92:93] offset0:97 offset1:113
	ds_write2_b64 v75, v[86:87], v[94:95] offset0:227 offset1:243
	ds_write2_b64 v75, v[100:101], v[108:109] offset0:129 offset1:145
	ds_write2_b64 v75, v[78:79], v[76:77] offset0:194 offset1:210
	v_add_u32_e32 v75, 0x2000, v49
	s_waitcnt lgkmcnt(0)
	ds_read2_b64 v[76:79], v75 offset0:32 offset1:97
	ds_read2_b64 v[80:83], v75 offset0:162 offset1:227
	v_add_u32_e32 v75, 0x2800, v49
	ds_read2_b64 v[84:87], v75 offset0:36 offset1:101
	ds_read2_b64 v[88:91], v75 offset0:166 offset1:231
	v_add_u32_e32 v75, 0x3000, v49
	ds_read2_b64 v[92:95], v75 offset0:40 offset1:105
	ds_read2_b64 v[96:99], v75 offset0:170 offset1:235
	v_add_u32_e32 v49, 0x3800, v49
	ds_read2_b64 v[100:103], v49 offset0:44 offset1:109
	ds_read2_b64 v[104:107], v49 offset0:174 offset1:239
	s_waitcnt lgkmcnt(7)
	v_mul_f32_e32 v108, v53, v69
	v_mul_f32_e32 v109, v53, v68
	v_fma_f32 v108, v52, v68, -v108
	v_fmac_f32_e32 v109, v52, v69
	v_add_f32_e32 v68, v108, v76
	v_add_f32_e32 v69, v109, v77
	v_mul_f32_e32 v108, v53, v69
	v_mul_f32_e32 v109, v53, v68
	v_fma_f32 v108, v52, v68, -v108
	v_fmac_f32_e32 v109, v52, v69
	v_add_f32_e32 v68, v108, v78
	v_add_f32_e32 v69, v109, v79
	s_waitcnt lgkmcnt(6)
	v_mul_f32_e32 v108, v53, v69
	v_mul_f32_e32 v109, v53, v68
	v_fma_f32 v108, v52, v68, -v108
	v_fmac_f32_e32 v109, v52, v69
	v_add_f32_e32 v68, v108, v80
	v_add_f32_e32 v69, v109, v81
	v_mul_f32_e32 v108, v53, v69
	v_mul_f32_e32 v109, v53, v68
	v_fma_f32 v108, v52, v68, -v108
	v_fmac_f32_e32 v109, v52, v69
	v_add_f32_e32 v68, v108, v82
	v_add_f32_e32 v69, v109, v83
	s_waitcnt lgkmcnt(5)
	v_mul_f32_e32 v108, v53, v69
	v_mul_f32_e32 v109, v53, v68
	v_fma_f32 v108, v52, v68, -v108
	v_fmac_f32_e32 v109, v52, v69
	v_add_f32_e32 v68, v108, v84
	v_add_f32_e32 v69, v109, v85
	v_mul_f32_e32 v108, v53, v69
	v_mul_f32_e32 v109, v53, v68
	v_fma_f32 v108, v52, v68, -v108
	v_fmac_f32_e32 v109, v52, v69
	v_add_f32_e32 v68, v108, v86
	v_add_f32_e32 v69, v109, v87
	s_waitcnt lgkmcnt(4)
	v_mul_f32_e32 v108, v53, v69
	v_mul_f32_e32 v109, v53, v68
	v_fma_f32 v108, v52, v68, -v108
	v_fmac_f32_e32 v109, v52, v69
	v_add_f32_e32 v68, v108, v88
	v_add_f32_e32 v69, v109, v89
	v_mul_f32_e32 v108, v53, v69
	v_mul_f32_e32 v109, v53, v68
	v_fma_f32 v108, v52, v68, -v108
	v_fmac_f32_e32 v109, v52, v69
	v_add_f32_e32 v68, v108, v90
	v_add_f32_e32 v69, v109, v91
	s_waitcnt lgkmcnt(3)
	v_mul_f32_e32 v108, v53, v69
	v_mul_f32_e32 v109, v53, v68
	v_fma_f32 v108, v52, v68, -v108
	v_fmac_f32_e32 v109, v52, v69
	v_add_f32_e32 v68, v108, v92
	v_add_f32_e32 v69, v109, v93
	v_mul_f32_e32 v108, v53, v69
	v_mul_f32_e32 v109, v53, v68
	v_fma_f32 v108, v52, v68, -v108
	v_fmac_f32_e32 v109, v52, v69
	v_add_f32_e32 v68, v108, v94
	v_add_f32_e32 v69, v109, v95
	s_waitcnt lgkmcnt(2)
	v_mul_f32_e32 v108, v53, v69
	v_mul_f32_e32 v109, v53, v68
	v_fma_f32 v108, v52, v68, -v108
	v_fmac_f32_e32 v109, v52, v69
	v_add_f32_e32 v68, v108, v96
	v_add_f32_e32 v69, v109, v97
	v_mul_f32_e32 v108, v53, v69
	v_mul_f32_e32 v109, v53, v68
	v_fma_f32 v108, v52, v68, -v108
	v_fmac_f32_e32 v109, v52, v69
	v_add_f32_e32 v68, v108, v98
	v_add_f32_e32 v69, v109, v99
	s_waitcnt lgkmcnt(1)
	v_mul_f32_e32 v108, v53, v69
	v_mul_f32_e32 v109, v53, v68
	v_fma_f32 v108, v52, v68, -v108
	v_fmac_f32_e32 v109, v52, v69
	v_add_f32_e32 v68, v108, v100
	v_add_f32_e32 v69, v109, v101
	v_mul_f32_e32 v108, v53, v69
	v_mul_f32_e32 v109, v53, v68
	v_fma_f32 v108, v52, v68, -v108
	v_fmac_f32_e32 v109, v52, v69
	v_add_f32_e32 v68, v108, v102
	v_add_f32_e32 v69, v109, v103
	s_waitcnt lgkmcnt(0)
	v_mul_f32_e32 v108, v53, v69
	v_mul_f32_e32 v109, v53, v68
	v_fma_f32 v108, v52, v68, -v108
	v_fmac_f32_e32 v109, v52, v69
	v_add_f32_e32 v68, v108, v104
	v_add_f32_e32 v69, v109, v105
	v_mul_f32_e32 v108, v53, v69
	v_mul_f32_e32 v109, v53, v68
	v_fma_f32 v108, v52, v68, -v108
	v_fmac_f32_e32 v109, v52, v69
	v_add_f32_e32 v68, v108, v106
	v_add_f32_e32 v69, v109, v107
	s_cbranch_scc0 .LBB0_1464
	s_mov_b64 s[58:59], 0
	s_and_b64 vcc, exec, s[56:57]
	s_cbranch_vccz .LBB0_1461
	s_ashr_i32 s53, s52, 31
	s_mov_b32 s55, s29
	s_lshl_b64 s[6:7], s[52:53], 12
	s_lshl_b64 s[30:31], s[54:55], 6
	s_add_u32 s6, s30, s6
	s_addc_u32 s7, s31, s7
	s_or_b32 s6, s6, s4
	s_lshl_b64 s[6:7], s[6:7], 9
	s_add_i32 s26, s26, s66
	s_waitcnt vmcnt(3)
	v_lshl_add_u64 v[32:33], v[174:175], 0, s[6:7]
	s_cmpk_gt_i32 s26, 0x3ff
	global_store_dwordx2 v[32:33], v[68:69], off
	s_cbranch_scc0 .LBB0_1458

; #define LAS __attribute__((address_space(3)))
; template <bool PROJECT> ...
;     ...
;     for (int i = 0; i < 4; ++i) *(LAS f32x4*)(Uh + (16 * i + utt) * 16 + ucc) = uh[i];
;     if (half + 1 < nhalf) {
; #pragma unroll
;         for (int i = 0; i < 4; ++i) uh[i] = *(const f32x4*)(ubuf + (size_t)(row0 + 64 + 16 * i + utt) * D + g * 16 + ucc); }
;     asm volatile("s_waitcnt lgkmcnt(0)" ::: "memory"); __builtin_amdgcn_wave_barrier();
; #pragma unroll 1
;     for (int tl = 0; tl < 4; ++tl) {
;         const int t0 = 64 * half + 16 * tl; if (t0 >= ntok) break;
;         const int nsub = (ntok - t0) < 16 ? (ntok - t0) : 16;
;         LAS float* Ul = Uh + tl * 256;
;         {
;             const f32x4 a0 = *(const LAS f32x4*)(Ul + c * 16 + c0), a1 = *(const LAS f32x4*)(Ul + c * 16 + c0 + 4);
;             u32x4 wh; wh.x = cvt_pk_bf16(a0[0], a0[1]); wh.y = cvt_pk_bf16(a0[2], a0[3]); wh.z = cvt_pk_bf16(a1[0], a1[1]); wh.w = cvt_pk_bf16(a1[2], a1[3]);
;             u32x4 wl;
;             wl.x = cvt_pk_bf16(a0[0] - __uint_as_float(wh.x << 16), a0[1] - __uint_as_float(wh.x & 0xffff0000u)); wl.y = cvt_pk_bf16(a0[2] - __uint_as_float(wh.y << 16), a0[3] - __uint_as_float(wh.y & 0xffff0000u));
;             wl.z = cvt_pk_bf16(a1[0] - __uint_as_float(wh.z << 16), a1[1] - __uint_as_float(wh.z & 0xffff0000u)); wl.w = cvt_pk_bf16(a1[2] - __uint_as_float(wh.w << 16), a1[3] - __uint_as_float(wh.w & 0xffff0000u));
;             u32x4 wsel; wsel.x = part ? wl.x : wh.x; wsel.y = part ? wl.y : wh.y; wsel.z = part ? wl.z : wh.z; wsel.w = part ? wl.w : wh.w;
;             const bf16x8 aop = __builtin_bit_cast(bf16x8, wsel);
;             f32x4 br[4], bi[4];
; #pragma unroll
;             for (int i = 0; i < 4; ++i) {
;                 f32x4 zr = (f32x4){0.f, 0.f, 0.f, 0.f}, zi = zr;
;                 br[i] = __builtin_amdgcn_mfma_f32_16x16x32_bf16(aop, bop[0][i], zr, 0, 0, 0); bi[i] = __builtin_amdgcn_mfma_f32_16x16x32_bf16(aop, bop[1][i], zi, 0, 0, 0);
;             }
;             asm volatile("s_nop 15\n\ts_nop 15\n\ts_nop 15\n\ts_nop 15" : "+v"(br[0]), "+v"(br[1]), "+v"(br[2]), "+v"(br[3]), "+v"(bi[0]), "+v"(bi[1]), "+v"(bi[2]), "+v"(bi[3]), "+v"(wsel));
; #pragma unroll
;             for (int i = 0; i < 4; ++i)
; #pragma unroll
;                 for (int j = 0; j < 4; ++j) *(LAS f32x2v*)(BUl + (4 * tq + j) * BU_PITCH + 2 * (16 * i + c)) = (f32x2v){br[i][j], bi[i][j]};
.LBB0_1472:
	s_or_b64 exec, exec, s[54:55]
	s_waitcnt vmcnt(0)
	ds_write_b128 v198, v[48:51]
	ds_write_b128 v198, v[72:75] offset:1024
	ds_write_b128 v198, v[72:75] offset:2048
	ds_write_b128 v198, v[72:75] offset:3072
	s_waitcnt lgkmcnt(0)
	ds_read_b128 v[48:51], v62
	ds_read_b128 v[76:79], v62 offset:16
	s_waitcnt lgkmcnt(1)
	v_cvt_pk_bf16_f32 v52, v48, v49
	s_nop 0
	v_lshlrev_b32_e32 v80, 16, v52
	v_sub_f32_e32 v48, v48, v80
	v_and_b32_e32 v80, 0xffff0000, v52
	v_sub_f32_e32 v49, v49, v80
	v_cvt_pk_bf16_f32 v68, v50, v51
	s_waitcnt lgkmcnt(0)
	v_cvt_pk_bf16_f32 v69, v76, v77
	v_cvt_pk_bf16_f32 v71, v78, v79
	v_cvt_pk_bf16_f32 v48, v48, v49
	v_lshlrev_b32_e32 v49, 16, v68
	v_sub_f32_e32 v49, v50, v49
	v_and_b32_e32 v50, 0xffff0000, v68
	v_sub_f32_e32 v50, v51, v50
	v_cvt_pk_bf16_f32 v49, v49, v50
	v_lshlrev_b32_e32 v50, 16, v69
	v_and_b32_e32 v51, 0xffff0000, v69
	v_sub_f32_e32 v50, v76, v50
	v_sub_f32_e32 v51, v77, v51
	v_cvt_pk_bf16_f32 v50, v50, v51
	v_lshlrev_b32_e32 v51, 16, v71
	v_sub_f32_e32 v51, v78, v51
	v_and_b32_e32 v76, 0xffff0000, v71
	v_sub_f32_e32 v76, v79, v76
	v_cvt_pk_bf16_f32 v51, v51, v76
	v_cndmask_b32_e64 v48, v48, v52, s[46:47]
	v_cndmask_b32_e64 v49, v49, v68, s[46:47]
	v_cndmask_b32_e64 v50, v50, v69, s[46:47]
	v_cndmask_b32_e64 v51, v51, v71, s[46:47]
	s_nop 1
	v_mfma_f32_16x16x32_bf16 v[0:3], v[48:51], v[0:3], 0
	v_mfma_f32_16x16x32_bf16 v[4:7], v[48:51], v[4:7], 0
	v_mfma_f32_16x16x32_bf16 v[8:11], v[48:51], v[8:11], 0
	v_mfma_f32_16x16x32_bf16 v[12:15], v[48:51], v[12:15], 0
	v_mfma_f32_16x16x32_bf16 v[20:23], v[48:51], v[20:23], 0
	v_mfma_f32_16x16x32_bf16 v[28:31], v[48:51], v[28:31], 0
	v_mfma_f32_16x16x32_bf16 v[36:39], v[48:51], v[36:39], 0
	v_mfma_f32_16x16x32_bf16 v[44:47], v[48:51], v[44:47], 0
	s_nop 7
	s_nop 0
	v_mov_b32_e32 v48, v0
	v_mov_b32_e32 v49, v4
	v_add_u32_e32 v50, v169, v171
	ds_write_b64 v50, v[48:49] offset:8448
	v_mov_b32_e32 v4, v1
	v_add_u32_e32 v48, v169, v200
	v_mov_b32_e32 v0, v2
	v_mov_b32_e32 v1, v6
	ds_write_b64 v48, v[0:1] offset:8968
	v_mov_b32_e32 v6, v3
	v_mov_b32_e32 v0, v8
	v_mov_b32_e32 v1, v12
	ds_write_b64 v48, v[4:5] offset:8448
	ds_write_b64 v48, v[6:7] offset:9488
	ds_write_b64 v50, v[0:1] offset:8576
	v_mov_b32_e32 v0, v10
	v_mov_b32_e32 v1, v14
	v_mov_b32_e32 v12, v9
	ds_write_b64 v48, v[0:1] offset:9096
	v_mov_b32_e32 v14, v11
	v_mov_b32_e32 v0, v20
	v_mov_b32_e32 v1, v28
	ds_write_b64 v48, v[12:13] offset:8576
	ds_write_b64 v48, v[14:15] offset:9616
	ds_write_b64 v50, v[0:1] offset:8704
	v_mov_b32_e32 v0, v22
	v_mov_b32_e32 v1, v30
	v_mov_b32_e32 v28, v21
	ds_write_b64 v48, v[0:1] offset:9224
	v_mov_b32_e32 v30, v23
	v_mov_b32_e32 v0, v36
	v_mov_b32_e32 v1, v44
	ds_write_b64 v48, v[28:29] offset:8704
	ds_write_b64 v48, v[30:31] offset:9744
	ds_write_b64 v50, v[0:1] offset:8832
	v_mov_b32_e32 v44, v37
	v_mov_b32_e32 v0, v38
	v_mov_b32_e32 v1, v46
	v_mov_b32_e32 v46, v39
	v_add_u32_e32 v8, s27, v166
	ds_write_b64 v48, v[44:45] offset:8832
	ds_write_b64 v48, v[0:1] offset:9352
	ds_write_b64 v48, v[46:47] offset:9872
	v_add_u32_e32 v4, 0x2000, v8
	s_waitcnt lgkmcnt(0)
	ds_read2_b64 v[0:3], v4 offset0:32 offset1:97
	ds_read2_b64 v[4:7], v4 offset0:162 offset1:227
	v_mul_f32_e32 v20, v59, v56
	v_pk_fma_f32 v[20:21], v[58:59], v[56:57], v[20:21] op_sel:[0,1,0] op_sel_hi:[1,0,0]
	v_mul_f32_e32 v22, v59, v57
	v_add_u32_e32 v12, 0x2800, v8
	s_waitcnt lgkmcnt(1)
	v_pk_add_f32 v[20:21], v[20:21], v[0:1] op_sel:[0,1] op_sel_hi:[1,0]
	v_pk_fma_f32 v[22:23], v[58:59], v[56:57], v[22:23] op_sel_hi:[1,1,0] neg_lo:[0,0,1] neg_hi:[0,0,1]
	ds_read2_b64 v[8:11], v12 offset0:36 offset1:101
	ds_read2_b64 v[12:15], v12 offset0:166 offset1:231
	v_pk_add_f32 v[0:1], v[22:23], v[0:1]
	v_add_u32_e32 v28, s27, v164
	v_cvt_pk_bf16_f32 v22, v0, v20
	v_pk_mul_f32 v[20:21], v[58:59], v[20:21] op_sel_hi:[1,0]
	ds_write_b32 v28, v22 offset:4096
	v_pk_fma_f32 v[22:23], v[58:59], v[0:1], v[20:21] op_sel:[1,0,0] op_sel_hi:[0,1,1]
	v_pk_fma_f32 v[0:1], v[58:59], v[0:1], v[20:21] op_sel:[1,0,0] op_sel_hi:[0,0,1] neg_lo:[0,0,1] neg_hi:[0,0,1]
	v_mov_b32_e32 v23, v1
	v_pk_add_f32 v[0:1], v[2:3], v[22:23] op_sel:[1,0] op_sel_hi:[0,1]
	v_cvt_pk_bf16_f32 v2, v1, v0
	ds_write_b32 v28, v2 offset:4368
	v_mul_f32_e32 v2, v59, v1
	v_pk_fma_f32 v[2:3], v[58:59], v[0:1], v[2:3] op_sel_hi:[1,1,0]
	v_mul_f32_e32 v20, v59, v0
	s_waitcnt lgkmcnt(4)
	v_pk_add_f32 v[2:3], v[4:5], v[2:3] op_sel:[1,0] op_sel_hi:[0,1]
	v_pk_fma_f32 v[0:1], v[58:59], v[0:1], v[20:21] op_sel:[0,1,0] op_sel_hi:[1,0,0] neg_lo:[0,0,1] neg_hi:[0,0,1]
	s_nop 0
	v_pk_add_f32 v[0:1], v[4:5], v[0:1]
	s_nop 0
	v_cvt_pk_bf16_f32 v4, v0, v2
	v_pk_mul_f32 v[2:3], v[58:59], v[2:3] op_sel_hi:[1,0]
	ds_write_b32 v28, v4 offset:4640
	v_pk_fma_f32 v[4:5], v[58:59], v[0:1], v[2:3] op_sel:[1,0,0] op_sel_hi:[0,1,1]
	v_pk_fma_f32 v[0:1], v[58:59], v[0:1], v[2:3] op_sel:[1,0,0] op_sel_hi:[0,0,1] neg_lo:[0,0,1] neg_hi:[0,0,1]
	v_mov_b32_e32 v5, v1
	v_pk_add_f32 v[0:1], v[6:7], v[4:5] op_sel:[1,0] op_sel_hi:[0,1]
	v_cvt_pk_bf16_f32 v2, v1, v0
	ds_write_b32 v28, v2 offset:4912
	v_mul_f32_e32 v2, v59, v1
	v_pk_fma_f32 v[2:3], v[58:59], v[0:1], v[2:3] op_sel_hi:[1,1,0]
	v_mul_f32_e32 v4, v59, v0
	s_waitcnt lgkmcnt(5)
; __device__ __forceinline__ unsigned cvt_pk_bf16(float lo, float hi) { unsigned r; asm volatile("v_cvt_pk_bf16_f32 %0, %1, %2" : "=v"(r) : "v"(lo), "v"(hi)); return r; }
; #define LAS __attribute__((address_space(3)))
; template <bool PROJECT> ...
;     ...
;             for (int t = 0; t < 16; ++t) {
;                 const float nre = lre * hre - lim * him + bur[t], nim = lre * him + lim * hre + bui[t];
;                 if (t < nsub) { hre = nre; him = nim; }
;                 if (PROJECT) *(LAS unsigned*)(Xb + t * XB_PITCH + 2 * lane) = cvt_pk_bf16(hre, him);
;             }
;         }
;         if (PROJECT) {
;             asm volatile("s_waitcnt lgkmcnt(0)" ::: "memory"); __builtin_amdgcn_wave_barrier();
;             f32x4 y = (f32x4){0.f, 0.f, 0.f, 0.f};
; #pragma unroll
;             for (int ks = 0; ks < 4; ++ks) { const bf16x8 ax = *(const LAS bf16x8*)(Xb + c * XB_PITCH + 32 * ks + 8 * tq); y = __builtin_amdgcn_mfma_f32_16x16x32_bf16(ax, cop[ks], y, 0, 0, 0); }
; #pragma unroll
;             for (int i = 0; i < 4; ++i) { const int t = 4 * tq + i;
;                 if (t < nsub) { const float v = y[i] + dv * Ul[t * 16 + c];
;                     gbuf[(size_t)(row0 + t0 + t) * D + g * 16 + c] = (bf16_t)(cvt_pk_bf16(gelu_tanh(v), 0.f) & 0xffffu); } }
	v_pk_add_f32 v[2:3], v[8:9], v[2:3] op_sel:[1,0] op_sel_hi:[0,1]
	v_pk_fma_f32 v[0:1], v[58:59], v[0:1], v[4:5] op_sel:[0,1,0] op_sel_hi:[1,0,0] neg_lo:[0,0,1] neg_hi:[0,0,1]
	s_nop 0
	v_pk_add_f32 v[0:1], v[8:9], v[0:1]
	s_nop 0
	v_cvt_pk_bf16_f32 v4, v0, v2
	v_pk_mul_f32 v[2:3], v[58:59], v[2:3] op_sel_hi:[1,0]
	ds_write_b32 v28, v4 offset:5184
	v_pk_fma_f32 v[4:5], v[58:59], v[0:1], v[2:3] op_sel:[1,0,0] op_sel_hi:[0,1,1]
	v_pk_fma_f32 v[0:1], v[58:59], v[0:1], v[2:3] op_sel:[1,0,0] op_sel_hi:[0,0,1] neg_lo:[0,0,1] neg_hi:[0,0,1]
	v_mov_b32_e32 v5, v1
	v_pk_add_f32 v[0:1], v[10:11], v[4:5] op_sel:[1,0] op_sel_hi:[0,1]
	v_cvt_pk_bf16_f32 v2, v1, v0
	ds_write_b32 v28, v2 offset:5456
	v_mul_f32_e32 v2, v59, v1
	v_pk_fma_f32 v[2:3], v[58:59], v[0:1], v[2:3] op_sel_hi:[1,1,0]
	v_mul_f32_e32 v4, v59, v0
	s_waitcnt lgkmcnt(6)
	v_pk_add_f32 v[2:3], v[12:13], v[2:3] op_sel:[1,0] op_sel_hi:[0,1]
	v_pk_fma_f32 v[0:1], v[58:59], v[0:1], v[4:5] op_sel:[0,1,0] op_sel_hi:[1,0,0] neg_lo:[0,0,1] neg_hi:[0,0,1]
	s_nop 0
	v_pk_add_f32 v[0:1], v[12:13], v[0:1]
	s_nop 0
	v_cvt_pk_bf16_f32 v4, v0, v2
	v_pk_mul_f32 v[2:3], v[58:59], v[2:3] op_sel:[1,0] op_sel_hi:[0,0]
	ds_write_b32 v28, v4 offset:5728
	v_pk_fma_f32 v[4:5], v[58:59], v[0:1], v[2:3] neg_lo:[0,0,1] neg_hi:[0,0,1]
	v_pk_fma_f32 v[0:1], v[58:59], v[0:1], v[2:3] op_sel_hi:[1,0,1]
	s_nop 0
	v_mov_b32_e32 v5, v1
	v_pk_add_f32 v[4:5], v[14:15], v[4:5]
	v_add_u32_e32 v14, v199, v162
	v_cvt_pk_bf16_f32 v0, v4, v5
	ds_write_b32 v28, v0 offset:6000
	v_cvt_pk_bf16_f32 v0, v4, v5
	ds_write_b32 v28, v0 offset:6272
	v_cvt_pk_bf16_f32 v0, v4, v5
	ds_write_b32 v28, v0 offset:6544
	v_cvt_pk_bf16_f32 v0, v4, v5
	ds_write_b32 v28, v0 offset:6816
	v_cvt_pk_bf16_f32 v0, v4, v5
	ds_write_b32 v28, v0 offset:7088
	v_cvt_pk_bf16_f32 v0, v4, v5
	ds_write_b32 v28, v0 offset:7360
	v_cvt_pk_bf16_f32 v0, v4, v5
	ds_write_b32 v28, v0 offset:7632
	v_cvt_pk_bf16_f32 v0, v4, v5
	ds_write_b32 v28, v0 offset:7904
	v_cvt_pk_bf16_f32 v0, v4, v5
	ds_write_b32 v28, v0 offset:8176
	s_waitcnt lgkmcnt(0)
	ds_read_b128 v[0:3], v14 offset:4096
	ds_read_b128 v[6:9], v14 offset:4160
	s_waitcnt lgkmcnt(1)
	v_mfma_f32_16x16x32_bf16 v[0:3], v[0:3], v[16:19], 0
	ds_read_b128 v[10:13], v14 offset:4224
	s_waitcnt lgkmcnt(1)
	v_mfma_f32_16x16x32_bf16 v[0:3], v[6:9], v[24:27], v[0:3]
	ds_read_b128 v[6:9], v14 offset:4288
	s_waitcnt lgkmcnt(1)
	v_mfma_f32_16x16x32_bf16 v[0:3], v[10:13], v[32:35], v[0:3]
	s_waitcnt lgkmcnt(0)
	v_mfma_f32_16x16x32_bf16 v[0:3], v[6:9], v[40:43], v[0:3]
	s_and_saveexec_b64 s[54:55], s[46:47]
	s_cbranch_execz .LBB0_1469
	v_or_b32_e32 v52, s26, v152
	v_lshlrev_b64 v[8:9], 11, v[52:53]
	v_or_b32_e32 v52, s26, v151
	v_lshlrev_b64 v[10:11], 11, v[52:53]
	v_or_b32_e32 v52, s26, v61
	v_lshlrev_b64 v[12:13], 11, v[52:53]
	v_or_b32_e32 v52, s26, v150
	v_lshl_add_u64 v[6:7], s[40:41], 1, v[178:179]
	v_lshlrev_b64 v[14:15], 11, v[52:53]
	v_lshl_add_u64 v[8:9], v[6:7], 0, v[8:9]
	v_lshl_add_u64 v[10:11], v[6:7], 0, v[10:11]
	v_lshl_add_u64 v[12:13], v[6:7], 0, v[12:13]
	v_lshl_add_u64 v[6:7], v[6:7], 0, v[14:15]
	v_add_u32_e32 v14, v63, v60
	ds_read_b32 v14, v14
	s_waitcnt lgkmcnt(0)
	v_fma_f32 v0, v67, v14, v0
	v_mul_f32_e32 v14, 0x3d372713, v0
	v_mul_f32_e32 v14, v0, v14
	v_fma_f32 v14, v0, v14, v0
	v_mul_f32_e32 v14, 0x3f4c422a, v14
	v_add_f32_e32 v14, v14, v14
	v_mul_f32_e32 v14, 0x3fb8aa3b, v14
	v_exp_f32_e32 v14, v14
	v_mul_f32_e32 v0, 0.5, v0
	v_add_f32_e32 v14, 1.0, v14
	v_rcp_f32_e32 v14, v14
	s_nop 0
	v_fma_f32 v14, v14, -2.0, 1.0
	v_add_f32_e32 v14, 1.0, v14
	v_mul_f32_e32 v0, v0, v14
	v_cvt_pk_bf16_f32 v0, v0, v53
	global_store_short v[6:7], v0, off
	ds_read_b32 v0, v64
	s_waitcnt lgkmcnt(0)
	v_fma_f32 v0, v67, v0, v1
	v_mul_f32_e32 v1, 0x3d372713, v0
	v_mul_f32_e32 v1, v0, v1
	v_fma_f32 v1, v0, v1, v0
	v_mul_f32_e32 v1, 0x3f4c422a, v1
	v_add_f32_e32 v1, v1, v1
	v_mul_f32_e32 v1, 0x3fb8aa3b, v1
	v_exp_f32_e32 v1, v1
	v_mul_f32_e32 v0, 0.5, v0
	v_add_f32_e32 v1, 1.0, v1
	v_rcp_f32_e32 v1, v1
	s_nop 0
	v_fma_f32 v1, v1, -2.0, 1.0
	v_add_f32_e32 v1, 1.0, v1
	v_mul_f32_e32 v0, v0, v1
	v_cvt_pk_bf16_f32 v0, v0, v53
	global_store_short v[12:13], v0, off
	ds_read_b32 v0, v65
	s_waitcnt lgkmcnt(0)
	v_fma_f32 v0, v67, v0, v2
	v_mul_f32_e32 v1, 0x3d372713, v0
	v_mul_f32_e32 v1, v0, v1
	v_fma_f32 v1, v0, v1, v0
	v_mul_f32_e32 v1, 0x3f4c422a, v1
	v_add_f32_e32 v1, v1, v1
	v_mul_f32_e32 v1, 0x3fb8aa3b, v1
	v_exp_f32_e32 v1, v1
	v_mul_f32_e32 v0, 0.5, v0
	v_add_f32_e32 v1, 1.0, v1
	v_rcp_f32_e32 v1, v1
	s_nop 0
	v_fma_f32 v1, v1, -2.0, 1.0
	v_add_f32_e32 v1, 1.0, v1
	v_mul_f32_e32 v0, v0, v1
	v_cvt_pk_bf16_f32 v0, v0, v53
	global_store_short v[10:11], v0, off
	ds_read_b32 v0, v66
	s_waitcnt lgkmcnt(0)
	v_fmac_f32_e32 v3, v67, v0
	v_mul_f32_e32 v0, 0x3d372713, v3
	v_mul_f32_e32 v0, v3, v0
	v_fma_f32 v0, v3, v0, v3
	v_mul_f32_e32 v0, 0x3f4c422a, v0
	v_add_f32_e32 v0, v0, v0
	v_mul_f32_e32 v0, 0x3fb8aa3b, v0
	v_exp_f32_e32 v0, v0
	v_mul_f32_e32 v1, 0.5, v3
	v_add_f32_e32 v0, 1.0, v0
	v_rcp_f32_e32 v0, v0
	s_nop 0
	v_fma_f32 v0, v0, -2.0, 1.0
	v_add_f32_e32 v0, 1.0, v0
	v_mul_f32_e32 v0, v1, v0
	v_cvt_pk_bf16_f32 v0, v0, v53
	global_store_short v[8:9], v0, off
	s_branch .LBB0_1469

; template <bool PROJECT> ...
;     ...
;             const f32x4 a0 = *(const LAS f32x4*)(Ul + c * 16 + c0), a1 = *(const LAS f32x4*)(Ul + c * 16 + c0 + 4);
;             u32x4 wh; wh.x = cvt_pk_bf16(a0[0], a0[1]); wh.y = cvt_pk_bf16(a0[2], a0[3]); wh.z = cvt_pk_bf16(a1[0], a1[1]); wh.w = cvt_pk_bf16(a1[2], a1[3]);
;             u32x4 wl;
;             wl.x = cvt_pk_bf16(a0[0] - __uint_as_float(wh.x << 16), a0[1] - __uint_as_float(wh.x & 0xffff0000u)); wl.y = cvt_pk_bf16(a0[2] - __uint_as_float(wh.y << 16), a0[3] - __uint_as_float(wh.y & 0xffff0000u));
;             wl.z = cvt_pk_bf16(a1[0] - __uint_as_float(wh.z << 16), a1[1] - __uint_as_float(wh.z & 0xffff0000u)); wl.w = cvt_pk_bf16(a1[2] - __uint_as_float(wh.w << 16), a1[3] - __uint_as_float(wh.w & 0xffff0000u));
;             u32x4 wsel; wsel.x = part ? wl.x : wh.x; wsel.y = part ? wl.y : wh.y; wsel.z = part ? wl.z : wh.z; wsel.w = part ? wl.w : wh.w;
;             const bf16x8 aop = __builtin_bit_cast(bf16x8, wsel);
;             f32x4 br[4], bi[4];
; #pragma unroll
;             for (int i = 0; i < 4; ++i) {
;                 f32x4 zr = (f32x4){0.f, 0.f, 0.f, 0.f}, zi = zr;
;                 br[i] = __builtin_amdgcn_mfma_f32_16x16x32_bf16(aop, bop[0][i], zr, 0, 0, 0); bi[i] = __builtin_amdgcn_mfma_f32_16x16x32_bf16(aop, bop[1][i], zi, 0, 0, 0);
;             }
;             asm volatile("s_nop 15\n\ts_nop 15\n\ts_nop 15\n\ts_nop 15" : "+v"(br[0]), "+v"(br[1]), "+v"(br[2]), "+v"(br[3]), "+v"(bi[0]), "+v"(bi[1]), "+v"(bi[2]), "+v"(bi[3]), "+v"(wsel));
; #pragma unroll
;             for (int i = 0; i < 4; ++i)
; #pragma unroll
;                 for (int j = 0; j < 4; ++j) *(LAS f32x2v*)(BUl + (4 * tq + j) * BU_PITCH + 2 * (16 * i + c)) = (f32x2v){br[i][j], bi[i][j]};
;             asm volatile("s_waitcnt lgkmcnt(0)" ::: "memory"); __builtin_amdgcn_wave_barrier();
;         }
;         {
;             float bur[16], bui[16];
; #pragma unroll
;             for (int t = 0; t < 16; ++t) { const f32x2v bu = *(const LAS f32x2v*)(BUl + t * BU_PITCH + 2 * lane); bur[t] = bu.x; bui[t] = bu.y; }
; #pragma unroll
;             for (int t = 0; t < 16; ++t) {
;                 const float nre = lre * hre - lim * him + bur[t], nim = lre * him + lim * hre + bui[t];
;                 if (t < nsub) { hre = nre; him = nim; }
;                 if (PROJECT) *(LAS unsigned*)(Xb + t * XB_PITCH + 2 * lane) = cvt_pk_bf16(hre, him);
.LBB0_1543:
	ds_read_b128 v[112:115], v135
	ds_read_b128 v[136:139], v135 offset:16
	v_add_u32_e32 v135, 0x400, v135
	s_waitcnt lgkmcnt(1)
	v_cvt_pk_bf16_f32 v140, v112, v113
	s_nop 0
	v_lshlrev_b32_e32 v144, 16, v140
	v_sub_f32_e32 v112, v112, v144
	v_and_b32_e32 v144, 0xffff0000, v140
	v_sub_f32_e32 v113, v113, v144
	v_cvt_pk_bf16_f32 v141, v114, v115
	s_waitcnt lgkmcnt(0)
	v_cvt_pk_bf16_f32 v142, v136, v137
	v_cvt_pk_bf16_f32 v143, v138, v139
	v_cvt_pk_bf16_f32 v112, v112, v113
	v_lshlrev_b32_e32 v113, 16, v141
	v_sub_f32_e32 v113, v114, v113
	v_and_b32_e32 v114, 0xffff0000, v141
	v_sub_f32_e32 v114, v115, v114
	v_cvt_pk_bf16_f32 v113, v113, v114
	v_lshlrev_b32_e32 v114, 16, v142
	v_and_b32_e32 v115, 0xffff0000, v142
	v_sub_f32_e32 v114, v136, v114
	v_sub_f32_e32 v115, v137, v115
	v_cvt_pk_bf16_f32 v114, v114, v115
	v_lshlrev_b32_e32 v115, 16, v143
	v_sub_f32_e32 v115, v138, v115
	v_and_b32_e32 v136, 0xffff0000, v143
	v_sub_f32_e32 v136, v139, v136
	v_cvt_pk_bf16_f32 v115, v115, v136
	v_cndmask_b32_e64 v112, v112, v140, s[46:47]
	v_cndmask_b32_e64 v113, v113, v141, s[46:47]
	v_cndmask_b32_e64 v114, v114, v142, s[46:47]
	v_cndmask_b32_e64 v115, v115, v143, s[46:47]
	s_nop 1
	v_mfma_f32_16x16x32_bf16 v[136:139], v[112:115], v[48:51], 0
	v_mfma_f32_16x16x32_bf16 v[140:143], v[112:115], v[52:55], 0
	v_mfma_f32_16x16x32_bf16 v[144:147], v[112:115], v[56:59], 0
	v_mfma_f32_16x16x32_bf16 v[148:151], v[112:115], v[60:63], 0
	v_mfma_f32_16x16x32_bf16 v[152:155], v[112:115], v[64:67], 0
	v_mfma_f32_16x16x32_bf16 v[156:159], v[112:115], v[68:71], 0
	v_mfma_f32_16x16x32_bf16 v[204:207], v[112:115], v[72:75], 0
	v_mfma_f32_16x16x32_bf16 v[208:211], v[112:115], v[76:79], 0
	s_nop 7
	s_nop 0
	v_mov_b32_e32 v112, v136
	v_mov_b32_e32 v113, v140
	v_add_u32_e32 v114, v169, v171
	ds_write_b64 v114, v[112:113] offset:8448
	v_add_u32_e32 v115, v169, v200
	v_mov_b32_e32 v112, v138
	v_mov_b32_e32 v113, v142
	v_mov_b32_e32 v140, v137
	ds_write_b64 v115, v[112:113] offset:8968
	v_mov_b32_e32 v142, v139
	v_mov_b32_e32 v112, v144
	v_mov_b32_e32 v113, v148
	ds_write_b64 v115, v[140:141] offset:8448
	ds_write_b64 v115, v[142:143] offset:9488
	ds_write_b64 v114, v[112:113] offset:8576
	v_mov_b32_e32 v112, v146
	v_mov_b32_e32 v113, v150
	v_mov_b32_e32 v148, v145
	ds_write_b64 v115, v[112:113] offset:9096
	v_mov_b32_e32 v150, v147
	v_mov_b32_e32 v112, v152
	v_mov_b32_e32 v113, v156
	ds_write_b64 v115, v[148:149] offset:8576
	ds_write_b64 v115, v[150:151] offset:9616
	ds_write_b64 v114, v[112:113] offset:8704
	v_mov_b32_e32 v112, v154
	v_mov_b32_e32 v113, v158
	v_mov_b32_e32 v156, v153
	ds_write_b64 v115, v[112:113] offset:9224
	v_mov_b32_e32 v158, v155
	v_mov_b32_e32 v112, v204
	v_mov_b32_e32 v113, v208
	ds_write_b64 v115, v[156:157] offset:8704
	ds_write_b64 v115, v[158:159] offset:9744
	ds_write_b64 v114, v[112:113] offset:8832
	v_mov_b32_e32 v208, v205
	v_mov_b32_e32 v112, v206
	v_mov_b32_e32 v113, v210
	v_mov_b32_e32 v210, v207
	v_add_u32_e32 v156, s27, v166
	ds_write_b64 v115, v[208:209] offset:8832
	ds_write_b64 v115, v[112:113] offset:9352
	ds_write_b64 v115, v[210:211] offset:9872
	v_add_u32_e32 v136, 0x2000, v156
	s_waitcnt lgkmcnt(0)
	ds_read2_b64 v[112:115], v136 offset0:32 offset1:97
	ds_read2_b64 v[136:139], v136 offset0:162 offset1:227
	v_add_u32_e32 v144, 0x2800, v156
	v_add_u32_e32 v152, 0x3000, v156
	v_add_u32_e32 v180, 0x3800, v156
	ds_read2_b64 v[140:143], v144 offset0:36 offset1:101
	ds_read2_b64 v[144:147], v144 offset0:166 offset1:231
	ds_read2_b64 v[148:151], v152 offset0:40 offset1:105
	ds_read2_b64 v[152:155], v152 offset0:170 offset1:235
	ds_read2_b64 v[156:159], v180 offset0:44 offset1:109
	ds_read2_b64 v[204:207], v180 offset0:174 offset1:239
	v_add_u32_e32 v208, s27, v164
	s_waitcnt lgkmcnt(7)
	v_mul_f32_e32 v190, v187, v189
	v_mul_f32_e32 v191, v187, v188
	v_fma_f32 v190, v186, v188, -v190
	v_fmac_f32_e32 v191, v186, v189
	v_add_f32_e32 v188, v190, v112
	v_add_f32_e32 v189, v191, v113
	v_cvt_pk_bf16_f32 v180, v188, v189
	ds_write_b32 v208, v180 offset:4096
	v_mul_f32_e32 v190, v187, v189
	v_mul_f32_e32 v191, v187, v188
	v_fma_f32 v190, v186, v188, -v190
	v_fmac_f32_e32 v191, v186, v189
	v_add_f32_e32 v188, v190, v114
	v_add_f32_e32 v189, v191, v115
	v_cvt_pk_bf16_f32 v180, v188, v189
	ds_write_b32 v208, v180 offset:4368
	s_waitcnt lgkmcnt(8)
	v_mul_f32_e32 v190, v187, v189
	v_mul_f32_e32 v191, v187, v188
	v_fma_f32 v190, v186, v188, -v190
	v_fmac_f32_e32 v191, v186, v189
	v_add_f32_e32 v188, v190, v136
	v_add_f32_e32 v189, v191, v137
	v_cvt_pk_bf16_f32 v180, v188, v189
	ds_write_b32 v208, v180 offset:4640
	v_mul_f32_e32 v190, v187, v189
	v_mul_f32_e32 v191, v187, v188
	v_fma_f32 v190, v186, v188, -v190
	v_fmac_f32_e32 v191, v186, v189
	v_add_f32_e32 v188, v190, v138
	v_add_f32_e32 v189, v191, v139
	v_cvt_pk_bf16_f32 v180, v188, v189
	ds_write_b32 v208, v180 offset:4912
	s_waitcnt lgkmcnt(9)
	v_mul_f32_e32 v190, v187, v189
	v_mul_f32_e32 v191, v187, v188
	v_fma_f32 v190, v186, v188, -v190
	v_fmac_f32_e32 v191, v186, v189
	v_add_f32_e32 v188, v190, v140
	v_add_f32_e32 v189, v191, v141
	v_cvt_pk_bf16_f32 v180, v188, v189
	ds_write_b32 v208, v180 offset:5184
	v_mul_f32_e32 v190, v187, v189
	v_mul_f32_e32 v191, v187, v188
	v_fma_f32 v190, v186, v188, -v190
	v_fmac_f32_e32 v191, v186, v189
	v_add_f32_e32 v188, v190, v142
	v_add_f32_e32 v189, v191, v143
	v_cvt_pk_bf16_f32 v180, v188, v189
	ds_write_b32 v208, v180 offset:5456
	s_waitcnt lgkmcnt(10)
; __device__ __forceinline__ unsigned cvt_pk_bf16(float lo, float hi) { unsigned r; asm volatile("v_cvt_pk_bf16_f32 %0, %1, %2" : "=v"(r) : "v"(lo), "v"(hi)); return r; }
; #define LAS __attribute__((address_space(3)))
; template <bool PROJECT> ...
;     ...
;             for (int t = 0; t < 16; ++t) {
;                 const float nre = lre * hre - lim * him + bur[t], nim = lre * him + lim * hre + bui[t];
;                 if (t < nsub) { hre = nre; him = nim; }
;                 if (PROJECT) *(LAS unsigned*)(Xb + t * XB_PITCH + 2 * lane) = cvt_pk_bf16(hre, him);
;             }
;         }
;         if (PROJECT) {
;             asm volatile("s_waitcnt lgkmcnt(0)" ::: "memory"); __builtin_amdgcn_wave_barrier();
;             f32x4 y = (f32x4){0.f, 0.f, 0.f, 0.f};
; #pragma unroll
;             for (int ks = 0; ks < 4; ++ks) { const bf16x8 ax = *(const LAS bf16x8*)(Xb + c * XB_PITCH + 32 * ks + 8 * tq); y = __builtin_amdgcn_mfma_f32_16x16x32_bf16(ax, cop[ks], y, 0, 0, 0); }
; #pragma unroll
;             for (int i = 0; i < 4; ++i) { const int t = 4 * tq + i;
;                 if (t < nsub) { const float v = y[i] + dv * Ul[t * 16 + c];
;                     gbuf[(size_t)(row0 + t0 + t) * D + g * 16 + c] = (bf16_t)(cvt_pk_bf16(gelu_tanh(v), 0.f) & 0xffffu); } }
	v_mul_f32_e32 v190, v187, v189
	v_mul_f32_e32 v191, v187, v188
	v_fma_f32 v190, v186, v188, -v190
	v_fmac_f32_e32 v191, v186, v189
	v_add_f32_e32 v188, v190, v144
	v_add_f32_e32 v189, v191, v145
	v_cvt_pk_bf16_f32 v180, v188, v189
	ds_write_b32 v208, v180 offset:5728
	v_mul_f32_e32 v190, v187, v189
	v_mul_f32_e32 v191, v187, v188
	v_fma_f32 v190, v186, v188, -v190
	v_fmac_f32_e32 v191, v186, v189
	v_add_f32_e32 v188, v190, v146
	v_add_f32_e32 v189, v191, v147
	v_cvt_pk_bf16_f32 v180, v188, v189
	ds_write_b32 v208, v180 offset:6000
	s_waitcnt lgkmcnt(11)
	v_mul_f32_e32 v190, v187, v189
	v_mul_f32_e32 v191, v187, v188
	v_fma_f32 v190, v186, v188, -v190
	v_fmac_f32_e32 v191, v186, v189
	v_add_f32_e32 v188, v190, v148
	v_add_f32_e32 v189, v191, v149
	v_cvt_pk_bf16_f32 v180, v188, v189
	ds_write_b32 v208, v180 offset:6272
	v_mul_f32_e32 v190, v187, v189
	v_mul_f32_e32 v191, v187, v188
	v_fma_f32 v190, v186, v188, -v190
	v_fmac_f32_e32 v191, v186, v189
	v_add_f32_e32 v188, v190, v150
	v_add_f32_e32 v189, v191, v151
	v_cvt_pk_bf16_f32 v180, v188, v189
	ds_write_b32 v208, v180 offset:6544
	s_waitcnt lgkmcnt(12)
	v_mul_f32_e32 v190, v187, v189
	v_mul_f32_e32 v191, v187, v188
	v_fma_f32 v190, v186, v188, -v190
	v_fmac_f32_e32 v191, v186, v189
	v_add_f32_e32 v188, v190, v152
	v_add_f32_e32 v189, v191, v153
	v_cvt_pk_bf16_f32 v180, v188, v189
	ds_write_b32 v208, v180 offset:6816
	v_mul_f32_e32 v190, v187, v189
	v_mul_f32_e32 v191, v187, v188
	v_fma_f32 v190, v186, v188, -v190
	v_fmac_f32_e32 v191, v186, v189
	v_add_f32_e32 v188, v190, v154
	v_add_f32_e32 v189, v191, v155
	v_cvt_pk_bf16_f32 v180, v188, v189
	ds_write_b32 v208, v180 offset:7088
	s_waitcnt lgkmcnt(13)
	v_mul_f32_e32 v190, v187, v189
	v_mul_f32_e32 v191, v187, v188
	v_fma_f32 v190, v186, v188, -v190
	v_fmac_f32_e32 v191, v186, v189
	v_add_f32_e32 v188, v190, v156
	v_add_f32_e32 v189, v191, v157
	v_cvt_pk_bf16_f32 v180, v188, v189
	ds_write_b32 v208, v180 offset:7360
	v_mul_f32_e32 v190, v187, v189
	v_mul_f32_e32 v191, v187, v188
	v_fma_f32 v190, v186, v188, -v190
	v_fmac_f32_e32 v191, v186, v189
	v_add_f32_e32 v188, v190, v158
	v_add_f32_e32 v189, v191, v159
	v_cvt_pk_bf16_f32 v180, v188, v189
	ds_write_b32 v208, v180 offset:7632
	s_waitcnt lgkmcnt(14)
	v_mul_f32_e32 v190, v187, v189
	v_mul_f32_e32 v191, v187, v188
	v_fma_f32 v190, v186, v188, -v190
	v_fmac_f32_e32 v191, v186, v189
	v_add_f32_e32 v188, v190, v204
	v_add_f32_e32 v189, v191, v205
	v_cvt_pk_bf16_f32 v180, v188, v189
	ds_write_b32 v208, v180 offset:7904
	v_mul_f32_e32 v190, v187, v189
	v_mul_f32_e32 v191, v187, v188
	v_fma_f32 v190, v186, v188, -v190
	v_fmac_f32_e32 v191, v186, v189
	v_add_f32_e32 v188, v190, v206
	v_add_f32_e32 v189, v191, v207
	v_cvt_pk_bf16_f32 v180, v188, v189
	ds_write_b32 v208, v180 offset:8176
	v_add_u32_e32 v112, v199, v162
	s_waitcnt lgkmcnt(0)
	ds_read_b128 v[136:139], v112 offset:4096
	ds_read_b128 v[140:143], v112 offset:4160
	s_waitcnt lgkmcnt(1)
	v_mfma_f32_16x16x32_bf16 v[136:139], v[136:139], v[92:95], 0
	s_waitcnt lgkmcnt(0)
	v_mfma_f32_16x16x32_bf16 v[136:139], v[140:143], v[80:83], v[136:139]
	ds_read_b128 v[140:143], v112 offset:4224
	ds_read_b128 v[112:115], v112 offset:4288
	s_waitcnt lgkmcnt(1)
	v_mfma_f32_16x16x32_bf16 v[136:139], v[140:143], v[84:87], v[136:139]
	s_waitcnt lgkmcnt(0)
	v_mfma_f32_16x16x32_bf16 v[112:115], v[112:115], v[88:91], v[136:139]
	s_nop 5
	ds_read_b32 v136, v134
	s_waitcnt lgkmcnt(0)
	v_fma_f32 v112, v203, v136, v112
	v_mul_f32_e32 v136, 0x3d372713, v112
	v_mul_f32_e32 v136, v112, v136
	v_fma_f32 v136, v112, v136, v112
	v_mul_f32_e32 v136, 0x3f4c422a, v136
	v_add_f32_e32 v136, v136, v136
	v_mul_f32_e32 v136, 0x3fb8aa3b, v136
	v_exp_f32_e32 v136, v136
	v_mul_f32_e32 v112, 0.5, v112
	v_add_f32_e32 v136, 1.0, v136
	v_rcp_f32_e32 v136, v136
	s_nop 0
	v_fma_f32 v136, v136, -2.0, 1.0
	v_add_f32_e32 v136, 1.0, v136
	v_mul_f32_e32 v112, v112, v136
	v_add_u32_e32 v136, s4, v133
	v_ashrrev_i32_e32 v137, 31, v136
	v_lshlrev_b64 v[138:139], 11, v[136:137]
	v_cvt_pk_bf16_f32 v112, v112, v181
	v_lshl_add_u64 v[138:139], v[116:117], 0, v[138:139]
	global_store_short v[138:139], v112, off
	ds_read_b32 v112, v134 offset:64
	s_add_i32 s4, s4, 16
	s_cmp_lg_u32 s4, 64
	s_waitcnt lgkmcnt(0)
	v_fma_f32 v112, v203, v112, v113
	v_mul_f32_e32 v113, 0x3d372713, v112
	v_mul_f32_e32 v113, v112, v113
	v_fma_f32 v113, v112, v113, v112
	v_mul_f32_e32 v113, 0x3f4c422a, v113
	v_add_f32_e32 v113, v113, v113
	v_mul_f32_e32 v113, 0x3fb8aa3b, v113
	v_exp_f32_e32 v113, v113
	v_mul_f32_e32 v112, 0.5, v112
	v_add_f32_e32 v113, 1.0, v113
	v_rcp_f32_e32 v113, v113
	s_nop 0
	v_fma_f32 v113, v113, -2.0, 1.0
	v_add_f32_e32 v113, 1.0, v113
	v_mul_f32_e32 v112, v112, v113
	v_cvt_pk_bf16_f32 v137, v112, v181
	v_add_u32_e32 v112, 1, v136
	v_ashrrev_i32_e32 v113, 31, v112
	v_lshlrev_b64 v[112:113], 11, v[112:113]
	v_lshl_add_u64 v[112:113], v[116:117], 0, v[112:113]
	global_store_short v[112:113], v137, off
	ds_read_b32 v112, v134 offset:128
	s_waitcnt lgkmcnt(0)
	v_fma_f32 v112, v203, v112, v114
	v_mul_f32_e32 v113, 0x3d372713, v112
	v_mul_f32_e32 v113, v112, v113
	v_fma_f32 v113, v112, v113, v112
	v_mul_f32_e32 v113, 0x3f4c422a, v113
	v_add_f32_e32 v113, v113, v113
	v_mul_f32_e32 v113, 0x3fb8aa3b, v113
	v_exp_f32_e32 v113, v113
	v_mul_f32_e32 v112, 0.5, v112
	v_add_f32_e32 v113, 1.0, v113
	v_rcp_f32_e32 v113, v113
	s_nop 0
	v_fma_f32 v113, v113, -2.0, 1.0
	v_add_f32_e32 v113, 1.0, v113
	v_mul_f32_e32 v112, v112, v113
	v_cvt_pk_bf16_f32 v114, v112, v181
	v_add_u32_e32 v112, 2, v136
	v_ashrrev_i32_e32 v113, 31, v112
	v_lshlrev_b64 v[112:113], 11, v[112:113]
	v_lshl_add_u64 v[112:113], v[116:117], 0, v[112:113]
	global_store_short v[112:113], v114, off
	ds_read_b32 v112, v134 offset:192
	v_add_u32_e32 v134, 0x400, v134
	s_waitcnt lgkmcnt(0)
	v_fmac_f32_e32 v115, v203, v112
	v_mul_f32_e32 v112, 0x3d372713, v115
	v_mul_f32_e32 v112, v115, v112
	v_fma_f32 v112, v115, v112, v115
	v_mul_f32_e32 v112, 0x3f4c422a, v112
	v_add_f32_e32 v112, v112, v112
	v_mul_f32_e32 v112, 0x3fb8aa3b, v112
	v_exp_f32_e32 v112, v112
	v_mul_f32_e32 v113, 0.5, v115
	v_add_f32_e32 v112, 1.0, v112
	v_rcp_f32_e32 v112, v112
	s_nop 0
	v_fma_f32 v112, v112, -2.0, 1.0
	v_add_f32_e32 v112, 1.0, v112
	v_mul_f32_e32 v112, v113, v112
	v_cvt_pk_bf16_f32 v114, v112, v181
	v_add_u32_e32 v112, 3, v136
	v_ashrrev_i32_e32 v113, 31, v112
	v_lshlrev_b64 v[112:113], 11, v[112:113]
	v_lshl_add_u64 v[112:113], v[116:117], 0, v[112:113]
	global_store_short v[112:113], v114, off
	s_waitcnt lgkmcnt(0)
	s_cbranch_scc1 .LBB0_1543
	s_mov_b32 s4, 64
	s_andn2_b64 vcc, exec, s[28:29]
	s_mov_b64 s[48:49], 0
	s_cbranch_vccz .LBB0_1546
	s_mov_b64 s[28:29], -1
	s_branch .LBB0_1540

; __device__ __forceinline__ unsigned cvt_pk_bf16(float lo, float hi) { unsigned r; asm volatile("v_cvt_pk_bf16_f32 %0, %1, %2" : "=v"(r) : "v"(lo), "v"(hi)); return r; }
;     __device__ __forceinline__ float apply(const f32x4 acc, int row, int col, int fq) const {
;         const u32x2 g4 = *(const u32x2*)(gbuf + (size_t)row * D + col); const f32x4 av = acc + *(const f32x4*)(bglu + col);
;         u32x2 w; w.x = cvt_pk_bf16(__uint_as_float(g4.x << 16) * fast_sigmoid(av[0]), __uint_as_float(g4.x & 0xffff0000u) * fast_sigmoid(av[1]));
;         w.y = cvt_pk_bf16(__uint_as_float(g4.y << 16) * fast_sigmoid(av[2]), __uint_as_float(g4.y & 0xffff0000u) * fast_sigmoid(av[3]));
;         *(u32x2*)(zb + (size_t)row * D + col) = w; return 0.f;
;     }
; template <class SEpi>
; __device__ __forceinline__ void sample_gemm(LAS unsigned char* lds, const bf16_t* A, const bf16_t* Bt, int K, const SEpi& E, int wave, int lane) {
;     ...
;         for (int k0 = 0; k0 < nks; k0 += 4) {
;             bf16x8 af[4], bf[4][4];
; #pragma unroll
;             for (int u = 0; u < 4; ++u) { const int ks = (k0 + u < nks) ? k0 + u : k0;
;                 af[u] = *(const bf16x8*)(ap + 32 * ks);
; #pragma unroll
;                 for (int c = 0; c < 4; ++c) bf[u][c] = *(const bf16x8*)(bp + (size_t)(16 * c) * K + 32 * ks); }
; #pragma unroll
;             for (int u = 0; u < 4; ++u) if (k0 + u < nks) {
; #pragma unroll
;                 for (int c = 0; c < 4; ++c) acc[c] = __builtin_amdgcn_mfma_f32_16x16x32_bf16(bf[u][c], af[u], acc[c], 0, 0, 0); }
;         }
;         asm volatile("s_nop 15\n\ts_nop 15" : "+v"(acc[0]), "+v"(acc[1]), "+v"(acc[2]), "+v"(acc[3]));
; #pragma unroll
;         for (int c = 0; c < 4; ++c) red[(wave * 4 + c) * 64 + lane] = acc[c];
;         __syncthreads();
;         if (wave < 4) {
;             f32x4 t = red[wave * 64 + lane];
; #pragma unroll
;             for (int w = 1; w < 8; ++w) t += red[(w * 4 + wave) * 64 + lane];
;             float q = E.apply(t, row, 64 * cg + 16 * wave + 4 * fq, fq);
;             if (SEpi::HAS_SSQ) { q += __shfl_xor(q, 16); q += __shfl_xor(q, 32); if (fq == 0) P[wave * 16 + fr] = q; }
;         }
;         __syncthreads();
;         if (SEpi::HAS_SSQ && wave == 0 && lane < 16) E.ssq_out[(size_t)(MP + 16 * rt + lane) * 16 + cg] = (P[lane] + P[16 + lane]) + (P[32 + lane] + P[48 + lane]);
.LBB0_1625:
	s_and_b32 s27, s4, 0x3c0
	v_or_b32_e32 v0, s27, v161
	v_lshlrev_b32_e32 v0, 11, v0
	v_lshl_add_u64 v[8:9], v[4:5], 0, v[0:1]
	v_add_co_u32_e32 v46, vcc, 0x8000, v8
	s_and_b32 s6, s26, -16
	s_nop 0
	v_addc_co_u32_e32 v47, vcc, 0, v9, vcc
	v_add_u32_e32 v6, s6, v163
	global_load_dwordx4 v[12:15], v[8:9], off
	v_add_co_u32_e32 v48, vcc, 0x10000, v8
	v_ashrrev_i32_e32 v7, 31, v6
	s_nop 0
	v_addc_co_u32_e32 v49, vcc, 0, v9, vcc
	v_lshlrev_b64 v[6:7], 11, v[6:7]
	v_add_co_u32_e32 v50, vcc, 0x18000, v8
	v_lshl_add_u64 v[44:45], v[2:3], 0, v[6:7]
	s_nop 0
	v_addc_co_u32_e32 v51, vcc, 0, v9, vcc
	global_load_dwordx4 v[16:19], v[44:45], off
	global_load_dwordx4 v[20:23], v[46:47], off
	global_load_dwordx4 v[24:27], v[48:49], off
	global_load_dwordx4 v[28:31], v[8:9], off offset:64
	global_load_dwordx4 v[36:39], v[50:51], off
	global_load_dwordx4 v[32:35], v[44:45], off offset:64
	s_and_b64 vcc, exec, s[46:47]
	s_waitcnt vmcnt(3)
	v_mfma_f32_16x16x32_bf16 v[24:27], v[24:27], v[16:19], 0
	v_mfma_f32_16x16x32_bf16 v[12:15], v[12:15], v[16:19], 0
	v_mfma_f32_16x16x32_bf16 v[20:23], v[20:23], v[16:19], 0
	s_waitcnt vmcnt(1)
	v_mfma_f32_16x16x32_bf16 v[16:19], v[36:39], v[16:19], 0
	global_load_dwordx4 v[36:39], v[48:49], off offset:64
	s_waitcnt vmcnt(1)
	v_mfma_f32_16x16x32_bf16 v[12:15], v[28:31], v[32:35], v[12:15]
	global_load_dwordx4 v[28:31], v[46:47], off offset:64
	s_waitcnt vmcnt(0)
	v_mfma_f32_16x16x32_bf16 v[20:23], v[28:31], v[32:35], v[20:23]
	global_load_dwordx4 v[28:31], v[8:9], off offset:128
	global_load_dwordx4 v[40:43], v[44:45], off offset:128
	v_mfma_f32_16x16x32_bf16 v[24:27], v[36:39], v[32:35], v[24:27]
	global_load_dwordx4 v[36:39], v[50:51], off offset:64
	s_waitcnt vmcnt(1)
	v_mfma_f32_16x16x32_bf16 v[12:15], v[28:31], v[40:43], v[12:15]
	global_load_dwordx4 v[28:31], v[46:47], off offset:128
	s_waitcnt vmcnt(1)
	v_mfma_f32_16x16x32_bf16 v[16:19], v[36:39], v[32:35], v[16:19]
	global_load_dwordx4 v[32:35], v[48:49], off offset:128
	s_waitcnt vmcnt(1)
	v_mfma_f32_16x16x32_bf16 v[20:23], v[28:31], v[40:43], v[20:23]
	global_load_dwordx4 v[28:31], v[8:9], off offset:192
	s_waitcnt vmcnt(1)
	v_mfma_f32_16x16x32_bf16 v[24:27], v[32:35], v[40:43], v[24:27]
	global_load_dwordx4 v[32:35], v[44:45], off offset:192
	s_waitcnt vmcnt(0)
	v_mfma_f32_16x16x32_bf16 v[12:15], v[28:31], v[32:35], v[12:15]
	global_load_dwordx4 v[28:31], v[50:51], off offset:128
	s_waitcnt vmcnt(0)
	v_mfma_f32_16x16x32_bf16 v[16:19], v[28:31], v[40:43], v[16:19]
	global_load_dwordx4 v[28:31], v[46:47], off offset:192
	s_waitcnt vmcnt(0)
	v_mfma_f32_16x16x32_bf16 v[20:23], v[28:31], v[32:35], v[20:23]
	global_load_dwordx4 v[28:31], v[48:49], off offset:192
	s_waitcnt vmcnt(0)
	v_mfma_f32_16x16x32_bf16 v[24:27], v[28:31], v[32:35], v[24:27]
	global_load_dwordx4 v[28:31], v[50:51], off offset:192
	s_waitcnt vmcnt(0)
	v_mfma_f32_16x16x32_bf16 v[16:19], v[28:31], v[32:35], v[16:19]
	s_nop 7
	ds_write_b128 v10, v[12:15]
	s_nop 0
	ds_write_b128 v10, v[20:23] offset:1024
	s_nop 1
	ds_write_b128 v10, v[24:27] offset:2048
	s_nop 1
	ds_write_b128 v10, v[16:19] offset:3072
	s_waitcnt lgkmcnt(0)
	s_barrier
	s_cbranch_vccnz .LBB0_1624
	ds_read_b128 v[12:15], v11
	ds_read_b128 v[16:19], v11 offset:4096
	s_load_dwordx2 s[6:7], s[0:1], 0xb8
	s_waitcnt lgkmcnt(0)
	v_pk_add_f32 v[8:9], v[14:15], v[18:19]
	v_pk_add_f32 v[16:17], v[12:13], v[16:17]
	ds_read_b128 v[12:15], v11 offset:8192
	s_waitcnt lgkmcnt(0)
	v_pk_add_f32 v[8:9], v[8:9], v[14:15]
	v_pk_add_f32 v[16:17], v[16:17], v[12:13]
	ds_read_b128 v[12:15], v11 offset:12288
	s_waitcnt lgkmcnt(0)
	v_pk_add_f32 v[8:9], v[8:9], v[14:15]
	v_pk_add_f32 v[16:17], v[16:17], v[12:13]
	ds_read_b128 v[12:15], v11 offset:16384
	s_waitcnt lgkmcnt(0)
	v_pk_add_f32 v[8:9], v[8:9], v[14:15]
	v_pk_add_f32 v[16:17], v[16:17], v[12:13]
	ds_read_b128 v[12:15], v11 offset:20480
	s_waitcnt lgkmcnt(0)
	v_pk_add_f32 v[8:9], v[8:9], v[14:15]
	v_pk_add_f32 v[16:17], v[16:17], v[12:13]
	ds_read_b128 v[12:15], v11 offset:24576
	s_waitcnt lgkmcnt(0)
	v_pk_add_f32 v[8:9], v[8:9], v[14:15]
	v_pk_add_f32 v[16:17], v[16:17], v[12:13]
	ds_read_b128 v[12:15], v11 offset:28672
	s_waitcnt lgkmcnt(0)
	v_pk_add_f32 v[8:9], v[8:9], v[14:15]
	v_or_b32_e32 v14, s27, v196
	v_pk_add_f32 v[16:17], v[16:17], v[12:13]
	v_lshl_add_u64 v[12:13], s[34:35], 0, v[6:7]
	v_lshlrev_b32_e32 v0, 1, v14
	v_lshl_add_u64 v[12:13], v[12:13], 0, v[0:1]
	global_load_dwordx2 v[18:19], v[12:13], off
	v_lshlrev_b32_e32 v12, 2, v14
	global_load_dwordx4 v[12:15], v12, s[6:7]
	v_lshl_add_u64 v[6:7], s[36:37], 0, v[6:7]
	v_lshl_add_u64 v[6:7], v[6:7], 0, v[0:1]
	s_waitcnt vmcnt(0)
	v_pk_add_f32 v[14:15], v[8:9], v[14:15]
	v_pk_add_f32 v[8:9], v[16:17], v[12:13]
	v_lshlrev_b32_e32 v12, 16, v18
	v_mul_f32_e32 v8, 0xbfb8aa3b, v8
	v_exp_f32_e32 v8, v8
	v_mul_f32_e32 v9, 0xbfb8aa3b, v9
	v_exp_f32_e32 v9, v9
	v_mul_f32_e32 v13, 0xbfb8aa3b, v15
	v_add_f32_e32 v8, 1.0, v8
	v_rcp_f32_e32 v8, v8
	v_add_f32_e32 v9, 1.0, v9
	v_rcp_f32_e32 v9, v9
	v_exp_f32_e32 v13, v13
	v_mul_f32_e32 v8, v8, v12
	v_and_b32_e32 v12, 0xffff0000, v18
	v_mul_f32_e32 v9, v9, v12
	v_mul_f32_e32 v12, 0xbfb8aa3b, v14
	v_exp_f32_e32 v12, v12
	v_add_f32_e32 v13, 1.0, v13
	v_rcp_f32_e32 v13, v13
	v_cvt_pk_bf16_f32 v8, v8, v9
	v_add_f32_e32 v12, 1.0, v12
	v_rcp_f32_e32 v12, v12
	v_lshlrev_b32_e32 v9, 16, v19
	v_mul_f32_e32 v9, v12, v9
	v_and_b32_e32 v12, 0xffff0000, v19
	v_mul_f32_e32 v12, v13, v12
	v_cvt_pk_bf16_f32 v9, v9, v12
	global_store_dwordx2 v[6:7], v[8:9], off
	s_branch .LBB0_1624

; __device__ __forceinline__ unsigned cvt_pk_bf16(float lo, float hi) { unsigned r; asm volatile("v_cvt_pk_bf16_f32 %0, %1, %2" : "=v"(r) : "v"(lo), "v"(hi)); return r; }
;     __device__ __forceinline__ float apply(const f32x4 acc, int row, int col, int fq) const {
;         bf16_t* bp = xb + (size_t)row * D + col; const u32x2 r = *(const u32x2*)bp; f32x4 o;
;         o[0] = __uint_as_float(r.x << 16); o[1] = __uint_as_float(r.x & 0xffff0000u); o[2] = __uint_as_float(r.y << 16); o[3] = __uint_as_float(r.y & 0xffff0000u);
;         o += acc * scale;
;         u32x2 w; w.x = cvt_pk_bf16(o[0], o[1]); w.y = cvt_pk_bf16(o[2], o[3]); *(u32x2*)bp = w;
;         return (o[0] * o[0] + o[1] * o[1]) + (o[2] * o[2] + o[3] * o[3]);
;     }
; template <class SEpi>
; __device__ __forceinline__ void sample_gemm(LAS unsigned char* lds, const bf16_t* A, const bf16_t* Bt, int K, const SEpi& E, int wave, int lane) {
;     ...
;         for (int k0 = 0; k0 < nks; k0 += 4) {
;             bf16x8 af[4], bf[4][4];
; #pragma unroll
;             for (int u = 0; u < 4; ++u) { const int ks = (k0 + u < nks) ? k0 + u : k0;
;                 af[u] = *(const bf16x8*)(ap + 32 * ks);
; #pragma unroll
;                 for (int c = 0; c < 4; ++c) bf[u][c] = *(const bf16x8*)(bp + (size_t)(16 * c) * K + 32 * ks); }
; #pragma unroll
;             for (int u = 0; u < 4; ++u) if (k0 + u < nks) {
; #pragma unroll
;                 for (int c = 0; c < 4; ++c) acc[c] = __builtin_amdgcn_mfma_f32_16x16x32_bf16(bf[u][c], af[u], acc[c], 0, 0, 0); }
;         }
;         asm volatile("s_nop 15\n\ts_nop 15" : "+v"(acc[0]), "+v"(acc[1]), "+v"(acc[2]), "+v"(acc[3]));
; #pragma unroll
;         for (int c = 0; c < 4; ++c) red[(wave * 4 + c) * 64 + lane] = acc[c];
;         __syncthreads();
;         if (wave < 4) {
;             f32x4 t = red[wave * 64 + lane];
; #pragma unroll
;             for (int w = 1; w < 8; ++w) t += red[(w * 4 + wave) * 64 + lane];
;             float q = E.apply(t, row, 64 * cg + 16 * wave + 4 * fq, fq);
;             if (SEpi::HAS_SSQ) { q += __shfl_xor(q, 16); q += __shfl_xor(q, 32); if (fq == 0) P[wave * 16 + fr] = q; }
;         }
;         __syncthreads();
;         if (SEpi::HAS_SSQ && wave == 0 && lane < 16) E.ssq_out[(size_t)(MP + 16 * rt + lane) * 16 + cg] = (P[lane] + P[16 + lane]) + (P[32 + lane] + P[48 + lane]);
.LBB0_1722:
	s_and_b32 s5, s4, 15
	s_lshl_b32 s27, s5, 6
	v_or_b32_e32 v5, s27, v161
	v_lshlrev_b32_e32 v168, 11, v5
	v_lshl_add_u64 v[42:43], v[2:3], 0, v[168:169]
	s_mov_b32 s6, 0x8000
	s_and_b32 s26, s4, -16
	v_add_co_u32_e32 v46, vcc, s6, v42
	s_addk_i32 s26, 0x4000
	s_nop 0
	v_addc_co_u32_e32 v47, vcc, 0, v43, vcc
	s_mov_b32 s6, 0x10000
	v_or_b32_e32 v4, s26, v161
	global_load_dwordx4 v[10:13], v[42:43], off
	v_add_co_u32_e32 v48, vcc, s6, v42
	v_ashrrev_i32_e32 v5, 31, v4
	s_nop 0
	v_addc_co_u32_e32 v49, vcc, 0, v43, vcc
	s_mov_b32 s6, 0x18000
	v_lshlrev_b64 v[4:5], 11, v[4:5]
	v_add_co_u32_e32 v50, vcc, s6, v42
	v_lshl_add_u64 v[44:45], v[0:1], 0, v[4:5]
	s_nop 0
	v_addc_co_u32_e32 v51, vcc, 0, v43, vcc
	global_load_dwordx4 v[14:17], v[44:45], off
	global_load_dwordx4 v[18:21], v[46:47], off
	global_load_dwordx4 v[22:25], v[48:49], off
	global_load_dwordx4 v[26:29], v[42:43], off offset:64
	global_load_dwordx4 v[34:37], v[50:51], off
	global_load_dwordx4 v[30:33], v[44:45], off offset:64
	s_and_b64 vcc, exec, s[46:47]
	s_waitcnt vmcnt(3)
	v_mfma_f32_16x16x32_bf16 v[22:25], v[22:25], v[14:17], 0
	v_mfma_f32_16x16x32_bf16 v[10:13], v[10:13], v[14:17], 0
	v_mfma_f32_16x16x32_bf16 v[18:21], v[18:21], v[14:17], 0
	s_waitcnt vmcnt(1)
	v_mfma_f32_16x16x32_bf16 v[14:17], v[34:37], v[14:17], 0
	global_load_dwordx4 v[34:37], v[48:49], off offset:64
	s_waitcnt vmcnt(1)
	v_mfma_f32_16x16x32_bf16 v[10:13], v[26:29], v[30:33], v[10:13]
	global_load_dwordx4 v[26:29], v[46:47], off offset:64
	s_waitcnt vmcnt(0)
	v_mfma_f32_16x16x32_bf16 v[18:21], v[26:29], v[30:33], v[18:21]
	global_load_dwordx4 v[26:29], v[42:43], off offset:128
	global_load_dwordx4 v[38:41], v[44:45], off offset:128
	v_mfma_f32_16x16x32_bf16 v[22:25], v[34:37], v[30:33], v[22:25]
	global_load_dwordx4 v[34:37], v[50:51], off offset:64
	s_waitcnt vmcnt(1)
	v_mfma_f32_16x16x32_bf16 v[10:13], v[26:29], v[38:41], v[10:13]
	global_load_dwordx4 v[26:29], v[46:47], off offset:128
	s_waitcnt vmcnt(1)
	v_mfma_f32_16x16x32_bf16 v[14:17], v[34:37], v[30:33], v[14:17]
	global_load_dwordx4 v[30:33], v[48:49], off offset:128
	s_waitcnt vmcnt(1)
	v_mfma_f32_16x16x32_bf16 v[18:21], v[26:29], v[38:41], v[18:21]
	global_load_dwordx4 v[26:29], v[42:43], off offset:192
	s_waitcnt vmcnt(1)
	v_mfma_f32_16x16x32_bf16 v[22:25], v[30:33], v[38:41], v[22:25]
	global_load_dwordx4 v[30:33], v[44:45], off offset:192
	s_waitcnt vmcnt(0)
	v_mfma_f32_16x16x32_bf16 v[10:13], v[26:29], v[30:33], v[10:13]
	global_load_dwordx4 v[26:29], v[50:51], off offset:128
	s_waitcnt vmcnt(0)
	v_mfma_f32_16x16x32_bf16 v[14:17], v[26:29], v[38:41], v[14:17]
	global_load_dwordx4 v[26:29], v[46:47], off offset:192
	s_waitcnt vmcnt(0)
	v_mfma_f32_16x16x32_bf16 v[18:21], v[26:29], v[30:33], v[18:21]
	global_load_dwordx4 v[26:29], v[48:49], off offset:192
	s_waitcnt vmcnt(0)
	v_mfma_f32_16x16x32_bf16 v[22:25], v[26:29], v[30:33], v[22:25]
	global_load_dwordx4 v[26:29], v[50:51], off offset:192
	s_waitcnt vmcnt(0)
	v_mfma_f32_16x16x32_bf16 v[14:17], v[26:29], v[30:33], v[14:17]
	s_nop 7
	ds_write_b128 v7, v[10:13]
	s_nop 0
	ds_write_b128 v7, v[18:21] offset:1024
	s_nop 1
	ds_write_b128 v7, v[22:25] offset:2048
	s_nop 1
	ds_write_b128 v7, v[14:17] offset:3072
	s_waitcnt lgkmcnt(0)
	s_barrier
	s_cbranch_vccnz .LBB0_1726
	ds_read_b128 v[10:13], v8
	ds_read_b128 v[14:17], v8 offset:4096
	v_or_b32_e32 v9, s27, v196
	v_lshl_add_u64 v[4:5], s[22:23], 0, v[4:5]
	v_lshlrev_b32_e32 v168, 1, v9
	v_lshl_add_u64 v[4:5], v[4:5], 0, v[168:169]
	s_waitcnt lgkmcnt(0)
	v_pk_add_f32 v[16:17], v[12:13], v[16:17]
	v_pk_add_f32 v[14:15], v[10:11], v[14:15]
	ds_read_b128 v[10:13], v8 offset:8192
	s_waitcnt lgkmcnt(0)
	v_pk_add_f32 v[16:17], v[16:17], v[12:13]
	v_pk_add_f32 v[14:15], v[14:15], v[10:11]
	ds_read_b128 v[10:13], v8 offset:12288
	s_waitcnt lgkmcnt(0)
	v_pk_add_f32 v[16:17], v[16:17], v[12:13]
	v_pk_add_f32 v[14:15], v[14:15], v[10:11]
	ds_read_b128 v[10:13], v8 offset:16384
	s_waitcnt lgkmcnt(0)
	v_pk_add_f32 v[16:17], v[16:17], v[12:13]
	v_pk_add_f32 v[14:15], v[14:15], v[10:11]
	ds_read_b128 v[10:13], v8 offset:20480
	s_waitcnt lgkmcnt(0)
	v_pk_add_f32 v[16:17], v[16:17], v[12:13]
	v_pk_add_f32 v[14:15], v[14:15], v[10:11]
	ds_read_b128 v[10:13], v8 offset:24576
	s_waitcnt lgkmcnt(0)
	v_pk_add_f32 v[16:17], v[16:17], v[12:13]
	v_pk_add_f32 v[14:15], v[14:15], v[10:11]
	ds_read_b128 v[10:13], v8 offset:28672
	s_waitcnt lgkmcnt(0)
	v_pk_add_f32 v[10:11], v[14:15], v[10:11]
	global_load_dwordx2 v[14:15], v[4:5], off
	v_pk_add_f32 v[12:13], v[16:17], v[12:13]
	s_waitcnt vmcnt(0)
	v_lshlrev_b32_e32 v16, 16, v14
	v_and_b32_e32 v17, 0xffff0000, v14
	v_lshlrev_b32_e32 v14, 16, v15
	v_and_b32_e32 v15, 0xffff0000, v15
	v_pk_add_f32 v[12:13], v[12:13], v[14:15]
	v_pk_add_f32 v[10:11], v[10:11], v[16:17]
	s_nop 0
	v_cvt_pk_bf16_f32 v14, v10, v11
	v_cvt_pk_bf16_f32 v15, v12, v13
	global_store_dwordx2 v[4:5], v[14:15], off
	v_mul_f32_e32 v4, v11, v11
	v_mul_f32_e32 v5, v13, v13
	v_fmac_f32_e32 v4, v10, v10
	v_fmac_f32_e32 v5, v12, v12
	v_add_f32_e32 v4, v4, v5
	ds_bpermute_b32 v5, v112, v4
	s_waitcnt lgkmcnt(0)
	v_add_f32_e32 v4, v4, v5
	ds_bpermute_b32 v5, v113, v4
	s_and_saveexec_b64 s[36:37], s[38:39]
	s_cbranch_execz .LBB0_1725
	s_waitcnt lgkmcnt(0)
	v_add_f32_e32 v4, v4, v5
	ds_write_b32 v6, v4 offset:32768

; __device__ __forceinline__ unsigned cvt_pk_bf16(float lo, float hi) { unsigned r; asm volatile("v_cvt_pk_bf16_f32 %0, %1, %2" : "=v"(r) : "v"(lo), "v"(hi)); return r; }
;     __device__ __forceinline__ float apply(const f32x4 acc, int row, int col, int fq) const {
;         bf16_t* bp = xb + (size_t)row * D + col; const u32x2 r = *(const u32x2*)bp; f32x4 o;
;         o[0] = __uint_as_float(r.x << 16); o[1] = __uint_as_float(r.x & 0xffff0000u); o[2] = __uint_as_float(r.y << 16); o[3] = __uint_as_float(r.y & 0xffff0000u);
;         o += acc * scale;
;         u32x2 w; w.x = cvt_pk_bf16(o[0], o[1]); w.y = cvt_pk_bf16(o[2], o[3]); *(u32x2*)bp = w;
;         return (o[0] * o[0] + o[1] * o[1]) + (o[2] * o[2] + o[3] * o[3]);
;     }
; template <class SEpi>
; __device__ __forceinline__ void sample_gemm(LAS unsigned char* lds, const bf16_t* A, const bf16_t* Bt, int K, const SEpi& E, int wave, int lane) {
;     ...
;         for (int c = 0; c < 4; ++c) red[(wave * 4 + c) * 64 + lane] = acc[c];
;         __syncthreads();
;         if (wave < 4) {
;             f32x4 t = red[wave * 64 + lane];
; #pragma unroll
;             for (int w = 1; w < 8; ++w) t += red[(w * 4 + wave) * 64 + lane];
;             float q = E.apply(t, row, 64 * cg + 16 * wave + 4 * fq, fq);
;             if (SEpi::HAS_SSQ) { q += __shfl_xor(q, 16); q += __shfl_xor(q, 32); if (fq == 0) P[wave * 16 + fr] = q; }
;         }
;         __syncthreads();
;         if (SEpi::HAS_SSQ && wave == 0 && lane < 16) E.ssq_out[(size_t)(MP + 16 * rt + lane) * 16 + cg] = (P[lane] + P[16 + lane]) + (P[32 + lane] + P[48 + lane]);
.LBB0_1964:
	s_addk_i32 s27, 0x4000
	s_nop 7
	v_add_u32_e32 v20, s3, v28
	s_and_b64 vcc, exec, s[24:25]
	ds_write_b128 v20, v[0:3]
	ds_write_b128 v20, v[4:7] offset:1024
	ds_write_b128 v20, v[8:11] offset:2048
	ds_write_b128 v20, v[12:15] offset:3072
	s_waitcnt lgkmcnt(0)
	s_barrier
	s_cbranch_vccz .LBB0_1968
	v_add_u32_e32 v10, s4, v28
	ds_read_b128 v[0:3], v10
	ds_read_b128 v[4:7], v10 offset:4096
	v_or_b32_e32 v8, s27, v161
	v_ashrrev_i32_e32 v9, 31, v8
	s_waitcnt lgkmcnt(0)
	v_pk_add_f32 v[6:7], v[2:3], v[6:7]
	v_pk_add_f32 v[4:5], v[0:1], v[4:5]
	ds_read_b128 v[0:3], v10 offset:8192
	s_waitcnt lgkmcnt(0)
	v_pk_add_f32 v[6:7], v[6:7], v[2:3]
	v_pk_add_f32 v[4:5], v[4:5], v[0:1]
	ds_read_b128 v[0:3], v10 offset:12288
	s_waitcnt lgkmcnt(0)
	v_pk_add_f32 v[6:7], v[6:7], v[2:3]
	v_pk_add_f32 v[4:5], v[4:5], v[0:1]
	ds_read_b128 v[0:3], v10 offset:16384
	s_waitcnt lgkmcnt(0)
	v_pk_add_f32 v[6:7], v[6:7], v[2:3]
	v_pk_add_f32 v[4:5], v[4:5], v[0:1]
	ds_read_b128 v[0:3], v10 offset:20480
	s_waitcnt lgkmcnt(0)
	v_pk_add_f32 v[6:7], v[6:7], v[2:3]
	v_pk_add_f32 v[4:5], v[4:5], v[0:1]
	ds_read_b128 v[0:3], v10 offset:24576
	s_waitcnt lgkmcnt(0)
	v_pk_add_f32 v[6:7], v[6:7], v[2:3]
	v_pk_add_f32 v[4:5], v[4:5], v[0:1]
	ds_read_b128 v[0:3], v10 offset:28672
	s_waitcnt lgkmcnt(0)
	v_pk_add_f32 v[2:3], v[6:7], v[2:3]
	v_pk_add_f32 v[0:1], v[4:5], v[0:1]
	v_or_b32_e32 v6, s26, v196
	v_lshlrev_b64 v[4:5], 11, v[8:9]
	v_lshl_add_u64 v[4:5], s[22:23], 0, v[4:5]
	v_lshlrev_b32_e32 v162, 1, v6
	v_lshl_add_u64 v[4:5], v[4:5], 0, v[162:163]
	global_load_dwordx2 v[6:7], v[4:5], off
	s_waitcnt vmcnt(0)
	v_lshlrev_b32_e32 v8, 16, v6
	v_and_b32_e32 v9, 0xffff0000, v6
	v_lshlrev_b32_e32 v6, 16, v7
	v_and_b32_e32 v7, 0xffff0000, v7
	v_pk_fma_f32 v[0:1], v[0:1], 0.5, v[8:9] op_sel_hi:[1,0,1]
	v_pk_fma_f32 v[2:3], v[2:3], 0.5, v[6:7] op_sel_hi:[1,0,1]
	v_cvt_pk_bf16_f32 v6, v0, v1
	v_mul_f32_e32 v1, v1, v1
	v_fmac_f32_e32 v1, v0, v0
	v_mul_f32_e32 v0, v3, v3
	v_fmac_f32_e32 v0, v2, v2
	v_add_f32_e32 v0, v1, v0
	ds_bpermute_b32 v1, v112, v0
	v_cvt_pk_bf16_f32 v7, v2, v3
	global_store_dwordx2 v[4:5], v[6:7], off
	s_waitcnt lgkmcnt(0)
	v_add_f32_e32 v0, v0, v1
	ds_bpermute_b32 v1, v113, v0
	s_and_saveexec_b64 s[38:39], s[40:41]
	s_cbranch_execz .LBB0_1967
	s_waitcnt lgkmcnt(0)
	v_add_f32_e32 v0, v0, v1
	ds_write_b32 v29, v0 offset:32768
